# GEMM calls: static s_setprio 1 for the wave half that enters the K-loop first, reset at call end
# baseline (speedup 1.0000x reference)
; #define PG8_BAR __builtin_amdgcn_s_barrier()
;     __host__ __device__ bool next(int i, Unit& u) const {
;         const long L = (long)i * G + c; if (L >= nwg) return false;
;         int wgid = (int)L; { const int q = nwg / NXCD, r = nwg % NXCD, xcd = wgid % NXCD, off = wgid / NXCD; wgid = (xcd < r ? xcd * (q + 1) : r * (q + 1) + (xcd - r) * q) + off; }
;         const int nig = WGM * nN, gid = wgid / nig, fm = gid * WGM, gsz = (nM - fm) < WGM ? (nM - fm) : WGM;
;         u.pm = fm + ((wgid % nig) % gsz); u.pn = (wgid % nig) / gsz; return true;
; template <class Epi, class Sched, bool STAMP = false>
; __device__ __forceinline__ void gemm_phase(PG8_LAS unsigned char* lds, const Gemm g, const Sched& S, const Epi& E, unsigned long long* stamps) {
;     int tid_ = threadIdx.x; asm volatile("" : "+v"(tid_)); const int tid = tid_, wid = __builtin_amdgcn_readfirstlane(tid >> 6), lane = tid & 63, wr = wid >> 2, wc = wid & 3, fr = lane & 15, fq = lane >> 4;
;     const int K = g.K, nt = K / BK, LD = g.ld;
;     unsigned voffA[2], voffB[2];
; #pragma unroll
;     for (int i = 0; i < 2; ++i) { int R, C; stage_rc(tid * 16 + i * 8192, R, C); const int Rb = Epi::PERM ? ((R & ~31) + perm32(R & 31)) : R;
;         voffA[i] = (unsigned)(R * LD + C) * 2u; voffB[i] = (unsigned)(Rb * LD + C) * 2u; }
;     const size_t kstep = (size_t)(BK * 2);
;     const size_t hstep = (size_t)HALF * LD * 2;
;     const size_t tstep = 2 * hstep;
;     const unsigned ldsw = (unsigned)wid * 1024u;
;     const int aoff = lds_byte(wr * 64 + fr, fq * 8), boff = lds_byte(wc * 32 + fr, fq * 8);
;     ...
;     Unit cur, nxt; int ui = 0;
;     if (!S.next(0, cur)) return;
;     f32x4 acc[2][2][4][2];
; #pragma unroll
;     for (int a = 0; a < 2; ++a)
; #pragma unroll
;         for (int b = 0; b < 2; ++b)
; #pragma unroll
;             for (int m = 0; m < 4; ++m)
; #pragma unroll
;                 for (int n = 0; n < 2; ++n) acc[a][b][m][n] = (f32x4){0.f, 0.f, 0.f, 0.f};
;     bf16x8 At[4][2], B0[2][2], B1[2][2];
;     const char* cA = (const char*)g.A + (size_t)cur.pm * tstep; const char* cB = (const char*)g.Bt + (size_t)cur.pn * tstep;
;     S.a_ready(cur);
;     PG8_STAGE(PG8_SB(0, 0), cB, voffB); PG8_STAGE(PG8_SA(0, 0), cA, voffA); PG8_STAGE(PG8_SB(0, 1), cB + hstep, voffB); PG8_STAGE(PG8_SA(0, 1), cA + hstep, voffA);
;     if (wr == 1) PG8_BAR;
.LBB0_32:
	v_readlane_b32 s2, v242, 19
	s_cmp_lt_u32 s2, 14
	s_cselect_b64 s[0:1], -1, 0
	s_cmp_gt_u32 s2, 13
	v_writelane_b32 v242, s0, 35
	s_cselect_b64 s[34:35], -1, 0
	s_mov_b64 s[36:37], 0
	v_writelane_b32 v242, s1, 36
	s_and_b64 s[0:1], s[34:35], exec
	s_cselect_b32 s0, -14, 0
	s_add_i32 s65, s0, s2
	s_mov_b64 s[2:3], 0
	v_writelane_b32 v242, s2, 37
	s_mov_b64 s[0:1], -1
	s_cmp_lt_i32 s65, 6
	v_writelane_b32 v242, s3, 38
	v_writelane_b32 v242, s88, 39
	s_nop 1
	v_writelane_b32 v242, s89, 40
	s_cbranch_scc1 .LBB0_548
	s_cmp_gt_i32 s65, 8
	s_cbranch_scc0 .LBB0_52
	s_cmp_gt_i32 s65, 10
	s_cbranch_scc0 .LBB0_62
	s_cmp_gt_i32 s65, 11
	s_cbranch_scc0 .LBB0_63
	s_cmp_eq_u32 s65, 12
	s_cbranch_scc0 .LBB0_120
	s_mov_b32 s3, s87
	s_mov_b32 s2, s86
	s_mov_b32 s10, s90
	v_mov_b32_e32 v14, v184
	s_cmpk_gt_i32 s10, 0x43f
	v_readfirstlane_b32 s36, v14
	s_cbranch_scc1 .LBB0_49
	v_lshlrev_b32_e32 v0, 4, v14
	v_add_u32_e32 v1, 0x2000, v0
	v_ashrrev_i32_e32 v2, 31, v1
	v_lshrrev_b32_e32 v2, 22, v2
	v_add_u32_e32 v2, v1, v2
	v_ashrrev_i32_e32 v8, 10, v2
	v_mul_i32_i24_e32 v2, 0x400, v8
	v_sub_u32_e32 v1, v1, v2
	v_lshrrev_b32_e32 v2, 4, v1
	v_bitop3_b32 v1, v2, v1, 32 bitop3:0x6c
	v_ashrrev_i32_e32 v2, 31, v1
	v_lshrrev_b32_e32 v2, 26, v2
	v_add_u32_e32 v2, v1, v2
	v_lshlrev_b32_e32 v3, 3, v8
	v_ashrrev_i32_e32 v9, 6, v2
	v_and_b32_e32 v3, -16, v3
	v_add_u32_e32 v3, v9, v3
	v_and_b32_e32 v4, 3, v9
	s_mov_b32 s0, 0x1fffe0
	v_lshrrev_b32_e32 v5, 2, v3
	v_lshlrev_b32_e32 v6, 1, v3
	v_and_b32_e32 v2, 0xc0, v2
	v_and_or_b32 v4, v3, s0, v4
	v_and_b32_e32 v5, 4, v5
	v_and_b32_e32 v6, 24, v6
	v_sub_u32_e32 v1, v1, v2
	v_or3_b32 v4, v4, v5, v6
	v_lshlrev_b32_e32 v5, 5, v8
	v_ashrrev_i16_sdwa v1, v188, sext(v1) dst_sel:DWORD dst_unused:UNUSED_PAD src0_sel:DWORD src1_sel:BYTE_0
	v_and_b32_e32 v5, 32, v5
	v_bfe_i32 v10, v1, 0, 16
	v_add_lshl_u32 v1, v5, v10, 1
	v_lshl_add_u32 v148, v4, 11, v1
	v_lshl_add_u32 v150, v3, 11, v1
	v_bfe_i32 v1, v14, 27, 1
	v_lshrrev_b32_e32 v1, 22, v1
	v_add_u32_e32 v1, v0, v1
	v_and_b32_e32 v1, 0xfffffc00, v1
	v_sub_u32_e32 v0, v0, v1
	v_lshrrev_b32_e32 v1, 4, v0
	v_ashrrev_i32_e32 v2, 31, v14
	v_bitop3_b32 v0, v1, v0, 32 bitop3:0x6c
	v_lshrrev_b32_e32 v2, 26, v2
	v_ashrrev_i32_e32 v1, 31, v0
	v_add_u32_e32 v2, v14, v2
	s_add_u32 s37, s2, 0x2200000
	v_lshrrev_b32_e32 v1, 26, v1
	s_waitcnt lgkmcnt(0)
	v_ashrrev_i32_e32 v12, 6, v2
	s_addc_u32 s40, s3, 0
	v_add_u32_e32 v1, v0, v1
	v_lshlrev_b32_e32 v2, 3, v12
	s_add_u32 s41, s2, 0x1000000
	v_ashrrev_i32_e32 v11, 6, v1
	v_and_b32_e32 v2, -16, v2
	s_addc_u32 s42, s3, 0
	v_add_u32_e32 v2, v11, v2
	v_and_b32_e32 v3, 3, v11
	s_ashr_i32 s44, s10, 31
	v_and_or_b32 v3, v2, s0, v3
	s_lshr_b32 s0, s44, 29
	s_add_i32 s0, s10, s0
	s_ashr_i32 s4, s36, 6
	s_ashr_i32 s1, s0, 3
	s_and_b32 s0, s0, -8
	s_ashr_i32 s5, s36, 8
	s_lshl_b32 s43, s4, 10
	s_sub_i32 s0, s10, s0
	s_cmp_lt_i32 s0, 0
	s_movk_i32 s6, 0x89
	s_cselect_b32 s6, s6, 0x88
	s_mul_i32 s0, s6, s0
	s_add_i32 s0, s0, s1
	s_ashr_i32 s1, s0, 31
	s_lshr_b32 s1, s1, 25
	v_lshrrev_b32_e32 v4, 2, v2
	v_lshlrev_b32_e32 v5, 1, v2
	v_and_b32_e32 v1, 0xc0, v1
	s_add_i32 s1, s0, s1
	v_and_b32_e32 v4, 4, v4
	v_and_b32_e32 v5, 24, v5
	v_sub_u32_e32 v0, v0, v1
	s_ashr_i32 s6, s1, 7
	v_or3_b32 v3, v3, v4, v5
	v_lshlrev_b32_e32 v4, 5, v12
	v_ashrrev_i16_sdwa v0, v188, sext(v0) dst_sel:DWORD dst_unused:UNUSED_PAD src0_sel:DWORD src1_sel:BYTE_0
	s_lshl_b32 s6, s6, 3
	v_and_b32_e32 v4, 32, v4
	v_bfe_i32 v13, v0, 0, 16
	s_sub_i32 s7, 0x44, s6
	v_add_lshl_u32 v0, v4, v13, 1
	s_min_u32 s7, s7, 8
	s_and_b32 s1, s1, 0xffffff80
	v_lshl_add_u32 v128, v3, 11, v0
	s_sub_i32 s12, s0, s1
	v_cvt_f32_ubyte0_e32 v3, s7
	v_cvt_f32_i32_e32 v1, s12
	v_rcp_iflag_f32_e32 v4, v3
	v_lshl_add_u32 v152, v2, 11, v0
	s_ashr_i32 s0, s12, 30
	s_or_b32 s13, s0, 1
	v_mul_f32_e32 v0, v1, v4
	v_trunc_f32_e32 v0, v0
	v_fma_f32 v1, -v0, v3, v1
	v_cvt_i32_f32_e32 v0, v0
	v_cmp_ge_f32_e64 s[0:1], |v1|, v3
	s_and_b64 s[0:1], s[0:1], exec
	s_cselect_b32 s0, s13, 0
	v_readfirstlane_b32 s1, v0
	s_add_i32 s0, s1, s0
	s_mul_i32 s1, s0, s7
	s_sub_i32 s1, s12, s1
	s_sext_i32_i8 s1, s1
	s_add_i32 s22, s6, s1
	s_ashr_i32 s23, s22, 31
	s_bfe_i64 s[12:13], s[0:1], 0x80000
	s_lshl_b64 s[6:7], s[22:23], 19
	s_lshl_b64 s[12:13], s[12:13], 19
	s_add_u32 s26, s41, s12
	s_addc_u32 s27, s42, s13
	s_add_i32 s23, s43, 0
	s_add_i32 m0, s23, 0x10000
	v_mov_b32_e32 v149, v129
	global_load_lds_dwordx4 v128, s[26:27]
	s_add_i32 m0, s23, 0x12000
	s_add_u32 s24, s37, s6
	global_load_lds_dwordx4 v148, s[26:27]
	s_addc_u32 s25, s40, s7
	s_mov_b32 m0, s23
	s_add_i32 s45, s23, 0x2000
	global_load_lds_dwordx4 v152, s[24:25]
	s_mov_b32 m0, s45
	s_add_u32 s6, s26, 0x40000
	global_load_lds_dwordx4 v150, s[24:25]
	s_addc_u32 s7, s27, 0
	s_add_i32 m0, s23, 0x14000
	v_mov_b32_e32 v153, v129
	global_load_lds_dwordx4 v128, s[6:7]
	s_add_i32 m0, s23, 0x16000
	v_mov_b32_e32 v151, v129
	global_load_lds_dwordx4 v148, s[6:7]
	s_add_u32 s6, s24, 0x40000
	s_addc_u32 s7, s25, 0
	s_add_i32 s46, s23, 0x4000
	s_mov_b32 m0, s46
	s_add_i32 s47, s23, 0x6000
	global_load_lds_dwordx4 v152, s[6:7]
	s_mov_b32 m0, s47
	s_mov_b32 s63, s65
	global_load_lds_dwordx4 v150, s[6:7]
	v_lshl_add_u64 v[6:7], s[26:27], 0, v[128:129]
	v_lshl_add_u64 v[4:5], s[26:27], 0, v[148:149]
	v_lshl_add_u64 v[2:3], s[24:25], 0, v[152:153]
	s_cmp_lg_u32 s5, 1
	v_lshl_add_u64 v[0:1], s[24:25], 0, v[150:151]
	s_setprio 1
	s_cbranch_scc1 .LBB0_40
	s_barrier
	s_setprio 0

; #define PG8_STAGE(bufoff, gbase, voff) do { _Pragma("unroll") for (int _i = 0; _i < 2; ++_i) \
;         __builtin_amdgcn_global_load_lds((const unsigned*)((const char*)(gbase) + (voff)[_i]), (PG8_LAS unsigned*)(lds + (bufoff) + ldsw + _i * 8192), 16, 0, 0); } while (0)
; #define PG8_BAR __builtin_amdgcn_s_barrier()
; #define INP(p, i) ldp((p).tbl, i)
;     __device__ bool next(int i, pg8::Unit& u) const { if (i != 0 || !valid) return false; u.pm = pm; u.pn = pn; return true; }
; template <class Epi, class Sched, bool STAMP = false>
; __device__ __forceinline__ void gemm_phase(PG8_LAS unsigned char* lds, const Gemm g, const Sched& S, const Epi& E, unsigned long long* stamps) {
;     ...
;     for (int i = 0; i < 2; ++i) { int R, C; stage_rc(tid * 16 + i * 8192, R, C); const int Rb = Epi::PERM ? ((R & ~31) + perm32(R & 31)) : R;
;         voffA[i] = (unsigned)(R * LD + C) * 2u; voffB[i] = (unsigned)(Rb * LD + C) * 2u; }
;     const size_t kstep = (size_t)(BK * 2);
;     const size_t hstep = (size_t)HALF * LD * 2;
;     const size_t tstep = 2 * hstep;
;     const unsigned ldsw = (unsigned)wid * 1024u;
;     const int aoff = lds_byte(wr * 64 + fr, fq * 8), boff = lds_byte(wc * 32 + fr, fq * 8);
;     ...
;     Unit cur, nxt; int ui = 0;
;     if (!S.next(0, cur)) return;
;     f32x4 acc[2][2][4][2];
; #pragma unroll
;     for (int a = 0; a < 2; ++a)
; #pragma unroll
;         for (int b = 0; b < 2; ++b)
; #pragma unroll
;             for (int m = 0; m < 4; ++m)
; #pragma unroll
;                 for (int n = 0; n < 2; ++n) acc[a][b][m][n] = (f32x4){0.f, 0.f, 0.f, 0.f};
;     bf16x8 At[4][2], B0[2][2], B1[2][2];
;     const char* cA = (const char*)g.A + (size_t)cur.pm * tstep; const char* cB = (const char*)g.Bt + (size_t)cur.pn * tstep;
;     S.a_ready(cur);
;     PG8_STAGE(PG8_SB(0, 0), cB, voffB); PG8_STAGE(PG8_SA(0, 0), cA, voffA); PG8_STAGE(PG8_SB(0, 1), cB + hstep, voffB); PG8_STAGE(PG8_SA(0, 1), cA + hstep, voffA);
;     if (wr == 1) PG8_BAR;
; __global__ void __launch_bounds__(512, 2) mega_fwd(Params prm) {
;     ...
;         case 11: { GEMM_PRO; EpiResid E; E.X = p.out; E.XB = XB; E.rowss_out = rs_ffn; E.Xp0 = l == 0 ? INP(p, 0) : nullptr; E.Xs0 = l == 0 ? INP(p, 1) : nullptr;
;                    run_gemm(lds, (const bf16_t*)(ws + OFF_A), (const bf16_t*)(ws + OFF_WO), 1024, 1024, E, T_P);
.LBB0_129:
	s_add_u32 s60, s10, 0x5500000
	s_addc_u32 s61, s46, 0
	s_add_u32 s62, s10, 0xe00000
	s_addc_u32 s63, s46, 0
	s_and_b64 s[2:3], s[34:35], exec
	s_mov_b32 s2, 0x33000
	s_cselect_b32 s2, s2, 0x11000
	s_add_u32 s2, s10, s2
	s_addc_u32 s3, s46, 0
	s_add_u32 s2, s2, 0x2060000
	s_addc_u32 s3, s3, 0
	s_andn2_b64 vcc, exec, s[6:7]
	s_cbranch_vccnz .LBB0_209
	v_ashrrev_i32_e32 v1, 31, v9
	v_lshrrev_b32_e32 v1, 26, v1
	v_add_u32_e32 v1, v9, v1
	v_ashrrev_i32_e32 v8, 6, v1
	v_bfe_i32 v1, v9, 27, 1
	v_lshlrev_b32_e32 v0, 4, v9
	v_lshrrev_b32_e32 v1, 22, v1
	v_add_u32_e32 v1, v0, v1
	v_and_b32_e32 v1, 0xfffffc00, v1
	v_sub_u32_e32 v1, v0, v1
	v_lshrrev_b32_e32 v2, 4, v1
	v_bitop3_b32 v1, v2, v1, 32 bitop3:0x6c
	v_ashrrev_i32_e32 v3, 31, v1
	v_lshrrev_b32_e32 v3, 26, v3
	v_add_u32_e32 v3, v1, v3
	v_lshlrev_b32_e32 v2, 3, v8
	v_ashrrev_i32_e32 v10, 6, v3
	v_and_b32_e32 v3, 0xc0, v3
	v_and_b32_e32 v2, 0x1ffff0, v2
	v_lshlrev_b32_e32 v4, 5, v8
	v_sub_u32_e32 v1, v1, v3
	v_add_u32_e32 v2, v10, v2
	v_and_b32_e32 v11, 32, v4
	v_ashrrev_i16_sdwa v1, v188, sext(v1) dst_sel:DWORD dst_unused:UNUSED_PAD src0_sel:DWORD src1_sel:BYTE_0
	s_waitcnt lgkmcnt(0)
	v_bfe_i32 v12, v1, 0, 16
	v_lshl_or_b32 v1, v2, 10, v11
	v_add_u32_e32 v0, 0x2000, v0
	v_add_lshl_u32 v148, v1, v12, 1
	v_ashrrev_i32_e32 v1, 31, v0
	v_lshrrev_b32_e32 v1, 22, v1
	v_add_u32_e32 v1, v0, v1
	v_ashrrev_i32_e32 v13, 10, v1
	v_mul_i32_i24_e32 v1, 0x400, v13
	v_sub_u32_e32 v0, v0, v1
	v_lshrrev_b32_e32 v1, 4, v0
	v_bitop3_b32 v0, v1, v0, 32 bitop3:0x6c
	v_ashrrev_i32_e32 v2, 31, v0
	v_lshrrev_b32_e32 v2, 26, v2
	s_ashr_i32 s7, s53, 6
	s_ashr_i32 s31, s30, 31
	s_ashr_i32 s37, s36, 31
	s_ashr_i32 s6, s53, 8
	v_add_u32_e32 v2, v0, v2
	s_lshl_b32 s64, s7, 10
	s_lshl_b64 s[12:13], s[30:31], 19
	s_lshl_b64 s[14:15], s[36:37], 19
	v_lshlrev_b32_e32 v1, 3, v13
	v_ashrrev_i32_e32 v14, 6, v2
	v_and_b32_e32 v2, 0xc0, v2
	s_add_u32 s48, s62, s14
	v_and_b32_e32 v1, 0x1ffff0, v1
	v_lshlrev_b32_e32 v3, 5, v13
	v_sub_u32_e32 v0, v0, v2
	s_addc_u32 s49, s63, s15
	s_add_i32 s37, s64, 0
	v_add_u32_e32 v1, v14, v1
	v_and_b32_e32 v15, 32, v3
	v_ashrrev_i16_sdwa v0, v188, sext(v0) dst_sel:DWORD dst_unused:UNUSED_PAD src0_sel:DWORD src1_sel:BYTE_0
	s_add_i32 m0, s37, 0x10000
	v_bfe_i32 v16, v0, 0, 16
	v_lshl_or_b32 v0, v1, 10, v15
	global_load_lds_dwordx4 v148, s[48:49]
	s_add_i32 m0, s37, 0x12000
	v_add_lshl_u32 v150, v0, v16, 1
	s_add_u32 s44, s60, s12
	s_mov_b32 s75, s65
	global_load_lds_dwordx4 v150, s[48:49]
	s_addc_u32 s45, s61, s13
	s_mov_b32 m0, s37
	s_add_i32 s65, s37, 0x2000
	global_load_lds_dwordx4 v148, s[44:45]
	s_mov_b32 m0, s65
	s_add_u32 s12, s48, 0x40000
	global_load_lds_dwordx4 v150, s[44:45]
	s_addc_u32 s13, s49, 0
	s_add_i32 m0, s37, 0x14000
	v_mov_b32_e32 v149, v129
	global_load_lds_dwordx4 v148, s[12:13]
	s_add_i32 m0, s37, 0x16000
	v_mov_b32_e32 v151, v129
	global_load_lds_dwordx4 v150, s[12:13]
	s_add_u32 s12, s44, 0x40000
	s_addc_u32 s13, s45, 0
	s_add_i32 s76, s37, 0x4000
	s_mov_b32 m0, s76
	s_add_i32 s77, s37, 0x6000
	global_load_lds_dwordx4 v148, s[12:13]
	s_mov_b32 m0, s77
	v_lshl_add_u64 v[6:7], s[48:49], 0, v[148:149]
	global_load_lds_dwordx4 v150, s[12:13]
	v_lshl_add_u64 v[4:5], s[48:49], 0, v[150:151]
	v_lshl_add_u64 v[2:3], s[44:45], 0, v[148:149]
	s_cmp_lg_u32 s6, 1
	v_lshl_add_u64 v[0:1], s[44:45], 0, v[150:151]
	s_setprio 1
	s_cbranch_scc1 .LBB0_132
	s_barrier
	s_setprio 0

; #define PG8_STAGE(bufoff, gbase, voff) do { _Pragma("unroll") for (int _i = 0; _i < 2; ++_i) \
;         __builtin_amdgcn_global_load_lds((const unsigned*)((const char*)(gbase) + (voff)[_i]), (PG8_LAS unsigned*)(lds + (bufoff) + ldsw + _i * 8192), 16, 0, 0); } while (0)
; #define PG8_BAR __builtin_amdgcn_s_barrier()
; template <class Epi, class Sched, bool STAMP = false>
; __device__ __forceinline__ void gemm_phase(PG8_LAS unsigned char* lds, const Gemm g, const Sched& S, const Epi& E, unsigned long long* stamps) {
;     ...
;     for (int i = 0; i < 2; ++i) { int R, C; stage_rc(tid * 16 + i * 8192, R, C); const int Rb = Epi::PERM ? ((R & ~31) + perm32(R & 31)) : R;
;         voffA[i] = (unsigned)(R * LD + C) * 2u; voffB[i] = (unsigned)(Rb * LD + C) * 2u; }
;     const size_t kstep = (size_t)(BK * 2);
;     const size_t hstep = (size_t)HALF * LD * 2;
;     const size_t tstep = 2 * hstep;
;     const unsigned ldsw = (unsigned)wid * 1024u;
;     const int aoff = lds_byte(wr * 64 + fr, fq * 8), boff = lds_byte(wc * 32 + fr, fq * 8);
;     ...
;     Unit cur, nxt; int ui = 0;
;     if (!S.next(0, cur)) return;
;     f32x4 acc[2][2][4][2];
; #pragma unroll
;     for (int a = 0; a < 2; ++a)
; #pragma unroll
;         for (int b = 0; b < 2; ++b)
; #pragma unroll
;             for (int m = 0; m < 4; ++m)
; #pragma unroll
;                 for (int n = 0; n < 2; ++n) acc[a][b][m][n] = (f32x4){0.f, 0.f, 0.f, 0.f};
;     bf16x8 At[4][2], B0[2][2], B1[2][2];
;     const char* cA = (const char*)g.A + (size_t)cur.pm * tstep; const char* cB = (const char*)g.Bt + (size_t)cur.pn * tstep;
;     S.a_ready(cur);
;     PG8_STAGE(PG8_SB(0, 0), cB, voffB); PG8_STAGE(PG8_SA(0, 0), cA, voffA); PG8_STAGE(PG8_SB(0, 1), cB + hstep, voffB); PG8_STAGE(PG8_SA(0, 1), cA + hstep, voffA);
;     if (wr == 1) PG8_BAR;
; __device__ __forceinline__ void run_wo_sample_tasks(LAS unsigned char* lds, unsigned char* ws) {
;     const int t = bidx(); OneUnit S; S.valid = t < 64; const int u = (t >> 2) & 15, sl = t & 3; S.pm = 64 + (u >> 2); S.pn = u & 3;
;     pg8::Gemm g; g.A = (const bf16_t*)(ws + OFF_A) + sl * 256; g.Bt = (const bf16_t*)(ws + OFF_WO) + sl * 256; g.M = T_ALL; g.N = 1024; g.K = 256; g.ld = 1024;
;     EpiPartial EA; EA.PART = (float*)(ws + OFF_GPART) + (size_t)sl * 1024 * 1024; EA.ldp = 1024;
;     pg8::gemm_phase<EpiPartial, OneUnit, false>(lds, g, S, EA, nullptr);
.LBB0_209:
	s_mov_b32 s0, s90
	v_mov_b32_e32 v0, v184
	s_cmp_gt_i32 s0, 63
	s_nop 0
	v_readfirstlane_b32 s40, v0
	s_cbranch_scc1 .LBB0_217
	s_waitcnt lgkmcnt(0)
	v_lshlrev_b32_e32 v1, 4, v0
	v_add_u32_e32 v2, 0x2000, v1
	v_ashrrev_i32_e32 v3, 31, v2
	v_lshrrev_b32_e32 v3, 22, v3
	v_add_u32_e32 v3, v2, v3
	v_ashrrev_i32_e32 v3, 10, v3
	v_mul_i32_i24_e32 v4, 0x400, v3
	v_sub_u32_e32 v2, v2, v4
	v_lshrrev_b32_e32 v4, 4, v2
	v_bitop3_b32 v2, v4, v2, 32 bitop3:0x6c
	v_ashrrev_i32_e32 v4, 31, v2
	v_lshrrev_b32_e32 v4, 26, v4
	v_add_u32_e32 v4, v2, v4
	v_lshrrev_b32_e32 v5, 6, v4
	v_lshlrev_b32_e32 v6, 3, v3
	v_and_b32_e32 v4, 0xc0, v4
	v_and_b32_e32 v6, 0x1ffff0, v6
	v_lshlrev_b32_e32 v3, 5, v3
	v_sub_u32_e32 v2, v2, v4
	v_add_u32_e32 v5, v5, v6
	v_and_b32_e32 v3, 32, v3
	v_ashrrev_i16_sdwa v2, v188, sext(v2) dst_sel:DWORD dst_unused:UNUSED_PAD src0_sel:DWORD src1_sel:BYTE_0
	v_lshl_or_b32 v3, v5, 10, v3
	v_bfe_i32 v2, v2, 0, 16
	v_add_lshl_u32 v148, v3, v2, 1
	v_bfe_i32 v2, v0, 27, 1
	v_lshrrev_b32_e32 v2, 22, v2
	v_add_u32_e32 v2, v1, v2
	v_and_b32_e32 v2, 0xfffffc00, v2
	v_sub_u32_e32 v1, v1, v2
	v_lshrrev_b32_e32 v2, 4, v1
	s_and_b32 s43, s0, 3
	s_bfe_u32 s1, s0, 0x20004
	s_ashr_i32 s12, s40, 6
	v_bitop3_b32 v1, v2, v1, 32 bitop3:0x6c
	v_ashrrev_i32_e32 v4, 31, v0
	s_or_b32 s42, s1, 64
	s_bfe_u32 s41, s0, 0x20002
	s_ashr_i32 s13, s40, 8
	s_lshl_b32 s44, s12, 10
	s_lshl_b32 s0, s43, 9
	v_ashrrev_i32_e32 v2, 31, v1
	v_lshrrev_b32_e32 v4, 26, v4
	s_add_u32 s1, s62, s0
	v_lshrrev_b32_e32 v2, 26, v2
	v_add_u32_e32 v4, v0, v4
	s_addc_u32 s4, s63, 0
	v_add_u32_e32 v2, v1, v2
	v_ashrrev_i32_e32 v4, 6, v4
	s_add_u32 s5, s60, s0
	v_lshrrev_b32_e32 v3, 6, v2
	v_lshlrev_b32_e32 v5, 3, v4
	v_and_b32_e32 v2, 0xc0, v2
	s_addc_u32 s6, s61, 0
	v_and_b32_e32 v5, 0x1ffff0, v5
	v_lshlrev_b32_e32 v4, 5, v4
	v_sub_u32_e32 v1, v1, v2
	s_lshl_b32 s7, s42, 19
	s_lshl_b32 s0, s41, 19
	v_add_u32_e32 v3, v3, v5
	v_and_b32_e32 v4, 32, v4
	v_ashrrev_i16_sdwa v1, v188, sext(v1) dst_sel:DWORD dst_unused:UNUSED_PAD src0_sel:DWORD src1_sel:BYTE_0
	s_add_u32 s0, s1, s0
	v_lshl_or_b32 v3, v3, 10, v4
	v_bfe_i32 v1, v1, 0, 16
	s_addc_u32 s1, s4, 0
	s_add_i32 s45, s44, 0
	v_add_lshl_u32 v128, v3, v1, 1
	s_add_i32 m0, s45, 0x10000
	s_mov_b32 s64, s65
	global_load_lds_dwordx4 v128, s[0:1]
	s_add_i32 m0, s45, 0x12000
	s_add_u32 s4, s5, s7
	global_load_lds_dwordx4 v148, s[0:1]
	s_addc_u32 s5, s6, 0
	s_mov_b32 m0, s45
	s_add_i32 s47, s45, 0x2000
	global_load_lds_dwordx4 v128, s[4:5]
	s_mov_b32 m0, s47
	s_add_u32 s6, s0, 0x40000
	global_load_lds_dwordx4 v148, s[4:5]
	s_addc_u32 s7, s1, 0
	s_add_i32 m0, s45, 0x14000
	s_nop 0
	global_load_lds_dwordx4 v128, s[6:7]
	s_add_i32 m0, s45, 0x16000
	s_nop 0
	global_load_lds_dwordx4 v148, s[6:7]
	s_add_u32 s6, s4, 0x40000
	s_addc_u32 s7, s5, 0
	s_add_i32 s48, s45, 0x4000
	s_mov_b32 m0, s48
	s_add_i32 s49, s45, 0x6000
	global_load_lds_dwordx4 v128, s[6:7]
	s_mov_b32 m0, s49
	s_cmp_lg_u32 s13, 1
	global_load_lds_dwordx4 v148, s[6:7]
	s_setprio 1
	s_cbranch_scc1 .LBB0_212
	s_barrier
	s_setprio 0

; #define PG8_STAGE(bufoff, gbase, voff) do { _Pragma("unroll") for (int _i = 0; _i < 2; ++_i) \
;         __builtin_amdgcn_global_load_lds((const unsigned*)((const char*)(gbase) + (voff)[_i]), (PG8_LAS unsigned*)(lds + (bufoff) + ldsw + _i * 8192), 16, 0, 0); } while (0)
; #define PG8_BAR __builtin_amdgcn_s_barrier()
;     __host__ __device__ bool next(int i, Unit& u) const {
;         const long L = (long)i * G + c; if (L >= nwg) return false;
;         int wgid = (int)L; { const int q = nwg / NXCD, r = nwg % NXCD, xcd = wgid % NXCD, off = wgid / NXCD; wgid = (xcd < r ? xcd * (q + 1) : r * (q + 1) + (xcd - r) * q) + off; }
;         const int nig = WGM * nN, gid = wgid / nig, fm = gid * WGM, gsz = (nM - fm) < WGM ? (nM - fm) : WGM;
;         u.pm = fm + ((wgid % nig) % gsz); u.pn = (wgid % nig) / gsz; return true;
; template <class Epi, class Sched, bool STAMP = false>
; __device__ __forceinline__ void gemm_phase(PG8_LAS unsigned char* lds, const Gemm g, const Sched& S, const Epi& E, unsigned long long* stamps) {
;     ...
;     for (int i = 0; i < 2; ++i) { int R, C; stage_rc(tid * 16 + i * 8192, R, C); const int Rb = Epi::PERM ? ((R & ~31) + perm32(R & 31)) : R;
;         voffA[i] = (unsigned)(R * LD + C) * 2u; voffB[i] = (unsigned)(Rb * LD + C) * 2u; }
;     const size_t kstep = (size_t)(BK * 2);
;     const size_t hstep = (size_t)HALF * LD * 2;
;     const size_t tstep = 2 * hstep;
;     const unsigned ldsw = (unsigned)wid * 1024u;
;     const int aoff = lds_byte(wr * 64 + fr, fq * 8), boff = lds_byte(wc * 32 + fr, fq * 8);
;     ...
;     Unit cur, nxt; int ui = 0;
;     if (!S.next(0, cur)) return;
;     f32x4 acc[2][2][4][2];
; #pragma unroll
;     for (int a = 0; a < 2; ++a)
; #pragma unroll
;         for (int b = 0; b < 2; ++b)
; #pragma unroll
;             for (int m = 0; m < 4; ++m)
; #pragma unroll
;                 for (int n = 0; n < 2; ++n) acc[a][b][m][n] = (f32x4){0.f, 0.f, 0.f, 0.f};
;     bf16x8 At[4][2], B0[2][2], B1[2][2];
;     const char* cA = (const char*)g.A + (size_t)cur.pm * tstep; const char* cB = (const char*)g.Bt + (size_t)cur.pn * tstep;
;     S.a_ready(cur);
;     PG8_STAGE(PG8_SB(0, 0), cB, voffB); PG8_STAGE(PG8_SA(0, 0), cA, voffA); PG8_STAGE(PG8_SB(0, 1), cB + hstep, voffB); PG8_STAGE(PG8_SA(0, 1), cA + hstep, voffA);
;     if (wr == 1) PG8_BAR;
.LBB0_283:
	v_bfe_i32 v1, v6, 27, 1
	v_lshlrev_b32_e32 v3, 4, v6
	v_lshrrev_b32_e32 v1, 22, v1
	v_ashrrev_i32_e32 v0, 31, v6
	v_add_u32_e32 v1, v3, v1
	v_lshrrev_b32_e32 v0, 26, v0
	v_and_b32_e32 v1, 0xfffffc00, v1
	v_add_u32_e32 v0, v6, v0
	v_sub_u32_e32 v1, v3, v1
	v_ashrrev_i32_e32 v0, 6, v0
	v_lshrrev_b32_e32 v2, 4, v1
	v_bitop3_b32 v2, v2, v1, 32 bitop3:0x6c
	v_lshlrev_b32_e32 v1, 3, v0
	v_and_b32_e32 v4, -16, v1
	v_ashrrev_i32_e32 v1, 31, v2
	v_lshrrev_b32_e32 v1, 26, v1
	s_waitcnt lgkmcnt(0)
	v_add_u32_e32 v5, v2, v1
	v_ashrrev_i32_e32 v1, 6, v5
	v_and_b32_e32 v5, 0xc0, v5
	v_sub_u32_e32 v2, v2, v5
	v_lshlrev_b32_e32 v7, 5, v0
	v_ashrrev_i16_sdwa v2, v188, sext(v2) dst_sel:DWORD dst_unused:UNUSED_PAD src0_sel:DWORD src1_sel:BYTE_0
	v_and_b32_e32 v7, 32, v7
	v_bfe_i32 v2, v2, 0, 16
	v_add_u32_e32 v4, v1, v4
	v_and_b32_e32 v9, 3, v1
	s_mov_b32 s3, 0x3fffe0
	v_add_lshl_u32 v7, v7, v2, 1
	v_lshlrev_b32_e32 v5, 1, v4
	v_lshrrev_b32_e32 v8, 2, v4
	v_and_or_b32 v9, v4, s3, v9
	v_lshl_add_u32 v148, v4, 10, v7
	v_add_u32_e32 v4, 0x2000, v3
	v_ashrrev_i32_e32 v3, 31, v4
	v_lshrrev_b32_e32 v3, 22, v3
	v_and_b32_e32 v5, 24, v5
	v_and_b32_e32 v8, 4, v8
	v_add_u32_e32 v3, v4, v3
	v_or3_b32 v5, v9, v8, v5
	v_ashrrev_i32_e32 v3, 10, v3
	v_lshl_add_u32 v128, v5, 10, v7
	v_mul_i32_i24_e32 v5, 0x400, v3
	v_sub_u32_e32 v4, v4, v5
	v_lshrrev_b32_e32 v5, 4, v4
	v_bitop3_b32 v5, v5, v4, 32 bitop3:0x6c
	v_lshlrev_b32_e32 v4, 3, v3
	v_and_b32_e32 v7, -16, v4
	v_ashrrev_i32_e32 v4, 31, v5
	v_lshrrev_b32_e32 v4, 26, v4
	v_add_u32_e32 v8, v5, v4
	v_ashrrev_i32_e32 v4, 6, v8
	v_add_u32_e32 v7, v4, v7
	v_and_b32_e32 v11, 3, v4
	s_add_i32 s2, s4, s2
	v_and_or_b32 v11, v7, s3, v11
	s_ashr_i32 s3, s2, 31
	s_lshr_b32 s3, s3, 27
	s_add_i32 s3, s2, s3
	s_ashr_i32 s4, s3, 5
	s_and_b32 s3, s3, 0xffe0
	s_sub_i32 s2, s2, s3
	s_bfe_i32 s3, s2, 0x80000
	s_bfe_u32 s3, s3, 0x3000c
	s_add_i32 s3, s2, s3
	s_lshl_b32 s7, s4, 3
	s_bfe_i32 s4, s3, 0x80000
	s_and_b32 s3, s3, 0xf8
	s_sub_i32 s2, s2, s3
	s_sext_i32_i16 s4, s4
	s_sext_i32_i8 s2, s2
	s_ashr_i32 s5, s36, 8
	s_lshr_b32 s4, s4, 3
	s_add_i32 s2, s7, s2
	s_ashr_i32 s6, s36, 6
	s_ashr_i32 s3, s2, 31
	s_bfe_i64 s[14:15], s[4:5], 0x100000
	v_and_b32_e32 v8, 0xc0, v8
	s_lshl_b32 s40, s6, 10
	s_lshl_b64 s[12:13], s[2:3], 18
	s_lshl_b64 s[14:15], s[14:15], 18
	v_sub_u32_e32 v5, v5, v8
	s_add_u32 s26, s44, s14
	v_lshlrev_b32_e32 v9, 5, v3
	v_ashrrev_i16_sdwa v5, v188, sext(v5) dst_sel:DWORD dst_unused:UNUSED_PAD src0_sel:DWORD src1_sel:BYTE_0
	v_lshlrev_b32_e32 v8, 1, v7
	v_lshrrev_b32_e32 v10, 2, v7
	s_addc_u32 s27, s45, s15
	s_add_i32 s3, s40, 0
	v_and_b32_e32 v9, 32, v9
	v_bfe_i32 v5, v5, 0, 16
	v_and_b32_e32 v8, 24, v8
	v_and_b32_e32 v10, 4, v10
	s_add_i32 m0, s3, 0x10000
	v_or3_b32 v8, v11, v10, v8
	v_add_lshl_u32 v9, v9, v5, 1
	global_load_lds_dwordx4 v128, s[26:27]
	s_add_i32 m0, s3, 0x12000
	v_lshl_add_u32 v152, v8, 10, v9
	s_add_u32 s24, s20, s12
	global_load_lds_dwordx4 v152, s[26:27]
	s_addc_u32 s25, s21, s13
	s_mov_b32 m0, s3
	s_add_i32 s41, s3, 0x2000
	v_lshl_add_u32 v150, v7, 10, v9
	global_load_lds_dwordx4 v148, s[24:25]
	s_mov_b32 m0, s41
	s_add_u32 s12, s26, 0x20000
	global_load_lds_dwordx4 v150, s[24:25]
	s_addc_u32 s13, s27, 0
	s_add_i32 m0, s3, 0x14000
	s_nop 0
	global_load_lds_dwordx4 v128, s[12:13]
	s_add_i32 m0, s3, 0x16000
	s_nop 0
	global_load_lds_dwordx4 v152, s[12:13]
	s_add_u32 s12, s24, 0x20000
	s_addc_u32 s13, s25, 0
	s_add_i32 s42, s3, 0x4000
	s_mov_b32 m0, s42
	s_add_i32 s43, s3, 0x6000
	global_load_lds_dwordx4 v148, s[12:13]
	s_mov_b32 m0, s43
	s_cmp_lg_u32 s5, 1
	global_load_lds_dwordx4 v150, s[12:13]
	s_setprio 1
	s_cbranch_scc1 .LBB0_285
	s_barrier
	s_setprio 0

; #define PG8_STAGE(bufoff, gbase, voff) do { _Pragma("unroll") for (int _i = 0; _i < 2; ++_i) \
;         __builtin_amdgcn_global_load_lds((const unsigned*)((const char*)(gbase) + (voff)[_i]), (PG8_LAS unsigned*)(lds + (bufoff) + ldsw + _i * 8192), 16, 0, 0); } while (0)
; #define PG8_BAR __builtin_amdgcn_s_barrier()
;     __host__ __device__ bool next(int i, Unit& u) const {
;         const long L = (long)i * G + c; if (L >= nwg) return false;
;         int wgid = (int)L; { const int q = nwg / NXCD, r = nwg % NXCD, xcd = wgid % NXCD, off = wgid / NXCD; wgid = (xcd < r ? xcd * (q + 1) : r * (q + 1) + (xcd - r) * q) + off; }
;         const int nig = WGM * nN, gid = wgid / nig, fm = gid * WGM, gsz = (nM - fm) < WGM ? (nM - fm) : WGM;
;         u.pm = fm + ((wgid % nig) % gsz); u.pn = (wgid % nig) / gsz; return true;
; template <class Epi, class Sched, bool STAMP = false>
; __device__ __forceinline__ void gemm_phase(PG8_LAS unsigned char* lds, const Gemm g, const Sched& S, const Epi& E, unsigned long long* stamps) {
;     ...
;     for (int i = 0; i < 2; ++i) { int R, C; stage_rc(tid * 16 + i * 8192, R, C); const int Rb = Epi::PERM ? ((R & ~31) + perm32(R & 31)) : R;
;         voffA[i] = (unsigned)(R * LD + C) * 2u; voffB[i] = (unsigned)(Rb * LD + C) * 2u; }
;     const size_t kstep = (size_t)(BK * 2);
;     const size_t hstep = (size_t)HALF * LD * 2;
;     const size_t tstep = 2 * hstep;
;     const unsigned ldsw = (unsigned)wid * 1024u;
;     const int aoff = lds_byte(wr * 64 + fr, fq * 8), boff = lds_byte(wc * 32 + fr, fq * 8);
;     ...
;     Unit cur, nxt; int ui = 0;
;     if (!S.next(0, cur)) return;
;     f32x4 acc[2][2][4][2];
; #pragma unroll
;     for (int a = 0; a < 2; ++a)
; #pragma unroll
;         for (int b = 0; b < 2; ++b)
; #pragma unroll
;             for (int m = 0; m < 4; ++m)
; #pragma unroll
;                 for (int n = 0; n < 2; ++n) acc[a][b][m][n] = (f32x4){0.f, 0.f, 0.f, 0.f};
;     bf16x8 At[4][2], B0[2][2], B1[2][2];
;     const char* cA = (const char*)g.A + (size_t)cur.pm * tstep; const char* cB = (const char*)g.Bt + (size_t)cur.pn * tstep;
;     S.a_ready(cur);
;     PG8_STAGE(PG8_SB(0, 0), cB, voffB); PG8_STAGE(PG8_SA(0, 0), cA, voffA); PG8_STAGE(PG8_SB(0, 1), cB + hstep, voffB); PG8_STAGE(PG8_SA(0, 1), cA + hstep, voffA);
;     if (wr == 1) PG8_BAR;
.LBB0_303:
	v_bfe_i32 v1, v6, 27, 1
	v_lshlrev_b32_e32 v3, 4, v6
	v_lshrrev_b32_e32 v1, 22, v1
	v_ashrrev_i32_e32 v0, 31, v6
	v_add_u32_e32 v1, v3, v1
	v_lshrrev_b32_e32 v0, 26, v0
	v_and_b32_e32 v1, 0xfffffc00, v1
	v_add_u32_e32 v0, v6, v0
	v_sub_u32_e32 v1, v3, v1
	v_ashrrev_i32_e32 v0, 6, v0
	v_lshrrev_b32_e32 v2, 4, v1
	v_bitop3_b32 v2, v2, v1, 32 bitop3:0x6c
	v_lshlrev_b32_e32 v1, 3, v0
	v_and_b32_e32 v4, -16, v1
	v_ashrrev_i32_e32 v1, 31, v2
	v_lshrrev_b32_e32 v1, 26, v1
	s_waitcnt lgkmcnt(0)
	v_add_u32_e32 v5, v2, v1
	v_ashrrev_i32_e32 v1, 6, v5
	v_and_b32_e32 v5, 0xc0, v5
	v_sub_u32_e32 v2, v2, v5
	v_lshlrev_b32_e32 v7, 5, v0
	v_ashrrev_i16_sdwa v2, v188, sext(v2) dst_sel:DWORD dst_unused:UNUSED_PAD src0_sel:DWORD src1_sel:BYTE_0
	v_and_b32_e32 v7, 32, v7
	v_bfe_i32 v2, v2, 0, 16
	v_add_u32_e32 v4, v1, v4
	v_and_b32_e32 v9, 3, v1
	s_mov_b32 s3, 0x1fffe0
	v_add_lshl_u32 v7, v7, v2, 1
	v_lshlrev_b32_e32 v5, 1, v4
	v_lshrrev_b32_e32 v8, 2, v4
	v_and_or_b32 v9, v4, s3, v9
	v_lshl_add_u32 v148, v4, 11, v7
	v_add_u32_e32 v4, 0x2000, v3
	v_ashrrev_i32_e32 v3, 31, v4
	v_lshrrev_b32_e32 v3, 22, v3
	v_and_b32_e32 v5, 24, v5
	v_and_b32_e32 v8, 4, v8
	v_add_u32_e32 v3, v4, v3
	v_or3_b32 v5, v9, v8, v5
	v_ashrrev_i32_e32 v3, 10, v3
	v_lshl_add_u32 v128, v5, 11, v7
	v_mul_i32_i24_e32 v5, 0x400, v3
	v_sub_u32_e32 v4, v4, v5
	v_lshrrev_b32_e32 v5, 4, v4
	v_bitop3_b32 v5, v5, v4, 32 bitop3:0x6c
	v_lshlrev_b32_e32 v4, 3, v3
	v_and_b32_e32 v7, -16, v4
	v_ashrrev_i32_e32 v4, 31, v5
	v_lshrrev_b32_e32 v4, 26, v4
	v_add_u32_e32 v8, v5, v4
	v_ashrrev_i32_e32 v4, 6, v8
	v_add_u32_e32 v7, v4, v7
	v_and_b32_e32 v11, 3, v4
	s_add_i32 s2, s4, s2
	v_and_or_b32 v11, v7, s3, v11
	s_ashr_i32 s3, s2, 31
	s_lshr_b32 s3, s3, 27
	s_add_i32 s3, s2, s3
	s_ashr_i32 s4, s3, 5
	s_and_b32 s3, s3, 0xffe0
	s_sub_i32 s2, s2, s3
	s_bfe_i32 s3, s2, 0x80000
	s_bfe_u32 s3, s3, 0x3000c
	s_add_i32 s3, s2, s3
	s_bfe_i32 s5, s3, 0x80000
	s_and_b32 s3, s3, 0xf8
	s_sub_i32 s2, s2, s3
	s_lshl_b32 s4, s4, 3
	s_sext_i32_i16 s5, s5
	s_sext_i32_i8 s2, s2
	s_ashr_i32 s7, s36, 8
	s_lshr_b32 s6, s5, 3
	s_add_i32 s2, s4, s2
	s_ashr_i32 s14, s36, 6
	s_ashr_i32 s3, s2, 31
	s_bfe_i64 s[12:13], s[6:7], 0x100000
	v_and_b32_e32 v8, 0xc0, v8
	s_lshl_b32 s56, s14, 10
	s_lshl_b64 s[4:5], s[2:3], 19
	s_lshl_b64 s[12:13], s[12:13], 19
	v_sub_u32_e32 v5, v5, v8
	s_add_u32 s12, s22, s12
	v_lshlrev_b32_e32 v9, 5, v3
	v_ashrrev_i16_sdwa v5, v188, sext(v5) dst_sel:DWORD dst_unused:UNUSED_PAD src0_sel:DWORD src1_sel:BYTE_0
	v_lshlrev_b32_e32 v8, 1, v7
	v_lshrrev_b32_e32 v10, 2, v7
	s_addc_u32 s13, s23, s13
	s_add_i32 s3, s56, 0
	v_and_b32_e32 v9, 32, v9
	v_bfe_i32 v5, v5, 0, 16
	v_and_b32_e32 v8, 24, v8
	v_and_b32_e32 v10, 4, v10
	s_add_i32 m0, s3, 0x10000
	v_or3_b32 v8, v11, v10, v8
	v_add_lshl_u32 v9, v9, v5, 1
	global_load_lds_dwordx4 v128, s[12:13]
	s_add_i32 m0, s3, 0x12000
	v_lshl_add_u32 v152, v8, 11, v9
	s_add_u32 s4, s42, s4
	global_load_lds_dwordx4 v152, s[12:13]
	s_addc_u32 s5, s43, s5
	s_mov_b32 m0, s3
	s_add_i32 s57, s3, 0x2000
	v_lshl_add_u32 v150, v7, 11, v9
	global_load_lds_dwordx4 v148, s[4:5]
	s_mov_b32 m0, s57
	s_add_u32 s16, s12, 0x40000
	global_load_lds_dwordx4 v150, s[4:5]
	s_addc_u32 s17, s13, 0
	s_add_i32 m0, s3, 0x14000
	s_nop 0
	global_load_lds_dwordx4 v128, s[16:17]
	s_add_i32 m0, s3, 0x16000
	s_nop 0
	global_load_lds_dwordx4 v152, s[16:17]
	s_add_u32 s16, s4, 0x40000
	s_addc_u32 s17, s5, 0
	s_add_i32 s58, s3, 0x4000
	s_mov_b32 m0, s58
	s_add_i32 s59, s3, 0x6000
	global_load_lds_dwordx4 v148, s[16:17]
	s_mov_b32 m0, s59
	s_cmp_lg_u32 s7, 1
	global_load_lds_dwordx4 v150, s[16:17]
	s_setprio 1
	s_cbranch_scc1 .LBB0_305
	s_barrier
	s_setprio 0

; #define PG8_STAGE(bufoff, gbase, voff) do { _Pragma("unroll") for (int _i = 0; _i < 2; ++_i) \
;         __builtin_amdgcn_global_load_lds((const unsigned*)((const char*)(gbase) + (voff)[_i]), (PG8_LAS unsigned*)(lds + (bufoff) + ldsw + _i * 8192), 16, 0, 0); } while (0)
; #define PG8_BAR __builtin_amdgcn_s_barrier()
;     __host__ __device__ bool next(int i, Unit& u) const {
;         const long L = (long)i * G + c; if (L >= nwg) return false;
;         int wgid = (int)L; { const int q = nwg / NXCD, r = nwg % NXCD, xcd = wgid % NXCD, off = wgid / NXCD; wgid = (xcd < r ? xcd * (q + 1) : r * (q + 1) + (xcd - r) * q) + off; }
;         const int nig = WGM * nN, gid = wgid / nig, fm = gid * WGM, gsz = (nM - fm) < WGM ? (nM - fm) : WGM;
;         u.pm = fm + ((wgid % nig) % gsz); u.pn = (wgid % nig) / gsz; return true;
; template <class Epi, class Sched, bool STAMP = false>
; __device__ __forceinline__ void gemm_phase(PG8_LAS unsigned char* lds, const Gemm g, const Sched& S, const Epi& E, unsigned long long* stamps) {
;     ...
;     for (int i = 0; i < 2; ++i) { int R, C; stage_rc(tid * 16 + i * 8192, R, C); const int Rb = Epi::PERM ? ((R & ~31) + perm32(R & 31)) : R;
;         voffA[i] = (unsigned)(R * LD + C) * 2u; voffB[i] = (unsigned)(Rb * LD + C) * 2u; }
;     const size_t kstep = (size_t)(BK * 2);
;     const size_t hstep = (size_t)HALF * LD * 2;
;     const size_t tstep = 2 * hstep;
;     const unsigned ldsw = (unsigned)wid * 1024u;
;     const int aoff = lds_byte(wr * 64 + fr, fq * 8), boff = lds_byte(wc * 32 + fr, fq * 8);
;     ...
;     Unit cur, nxt; int ui = 0;
;     if (!S.next(0, cur)) return;
;     f32x4 acc[2][2][4][2];
; #pragma unroll
;     for (int a = 0; a < 2; ++a)
; #pragma unroll
;         for (int b = 0; b < 2; ++b)
; #pragma unroll
;             for (int m = 0; m < 4; ++m)
; #pragma unroll
;                 for (int n = 0; n < 2; ++n) acc[a][b][m][n] = (f32x4){0.f, 0.f, 0.f, 0.f};
;     bf16x8 At[4][2], B0[2][2], B1[2][2];
;     const char* cA = (const char*)g.A + (size_t)cur.pm * tstep; const char* cB = (const char*)g.Bt + (size_t)cur.pn * tstep;
;     S.a_ready(cur);
;     PG8_STAGE(PG8_SB(0, 0), cB, voffB); PG8_STAGE(PG8_SA(0, 0), cA, voffA); PG8_STAGE(PG8_SB(0, 1), cB + hstep, voffB); PG8_STAGE(PG8_SA(0, 1), cA + hstep, voffA);
;     if (wr == 1) PG8_BAR;
.LBB0_323:
	v_bfe_i32 v1, v6, 27, 1
	v_lshlrev_b32_e32 v3, 4, v6
	v_lshrrev_b32_e32 v1, 22, v1
	v_ashrrev_i32_e32 v0, 31, v6
	v_add_u32_e32 v1, v3, v1
	v_lshrrev_b32_e32 v0, 26, v0
	v_and_b32_e32 v1, 0xfffffc00, v1
	v_add_u32_e32 v0, v6, v0
	v_sub_u32_e32 v1, v3, v1
	v_ashrrev_i32_e32 v0, 6, v0
	v_lshrrev_b32_e32 v2, 4, v1
	v_bitop3_b32 v2, v2, v1, 32 bitop3:0x6c
	v_lshlrev_b32_e32 v1, 3, v0
	v_and_b32_e32 v4, -16, v1
	v_ashrrev_i32_e32 v1, 31, v2
	v_lshrrev_b32_e32 v1, 26, v1
	s_waitcnt lgkmcnt(0)
	v_add_u32_e32 v5, v2, v1
	v_ashrrev_i32_e32 v1, 6, v5
	v_and_b32_e32 v5, 0xc0, v5
	v_sub_u32_e32 v2, v2, v5
	v_lshlrev_b32_e32 v7, 5, v0
	v_ashrrev_i16_sdwa v2, v188, sext(v2) dst_sel:DWORD dst_unused:UNUSED_PAD src0_sel:DWORD src1_sel:BYTE_0
	v_and_b32_e32 v7, 32, v7
	v_bfe_i32 v2, v2, 0, 16
	v_add_u32_e32 v4, v1, v4
	v_and_b32_e32 v9, 3, v1
	s_mov_b32 s3, 0x3fffe0
	v_add_lshl_u32 v7, v7, v2, 1
	v_lshlrev_b32_e32 v5, 1, v4
	v_lshrrev_b32_e32 v8, 2, v4
	v_and_or_b32 v9, v4, s3, v9
	v_lshl_add_u32 v148, v4, 10, v7
	v_add_u32_e32 v4, 0x2000, v3
	v_ashrrev_i32_e32 v3, 31, v4
	v_lshrrev_b32_e32 v3, 22, v3
	v_and_b32_e32 v5, 24, v5
	v_and_b32_e32 v8, 4, v8
	v_add_u32_e32 v3, v4, v3
	v_or3_b32 v5, v9, v8, v5
	v_ashrrev_i32_e32 v3, 10, v3
	v_lshl_add_u32 v128, v5, 10, v7
	v_mul_i32_i24_e32 v5, 0x400, v3
	v_sub_u32_e32 v4, v4, v5
	v_lshrrev_b32_e32 v5, 4, v4
	v_bitop3_b32 v5, v5, v4, 32 bitop3:0x6c
	v_lshlrev_b32_e32 v4, 3, v3
	v_and_b32_e32 v7, -16, v4
	v_ashrrev_i32_e32 v4, 31, v5
	v_lshrrev_b32_e32 v4, 26, v4
	v_add_u32_e32 v8, v5, v4
	v_ashrrev_i32_e32 v4, 6, v8
	v_add_u32_e32 v7, v4, v7
	v_and_b32_e32 v11, 3, v4
	s_add_i32 s2, s4, s2
	v_and_or_b32 v11, v7, s3, v11
	s_ashr_i32 s3, s2, 31
	s_lshr_b32 s3, s3, 27
	s_add_i32 s3, s2, s3
	s_ashr_i32 s4, s3, 5
	s_and_b32 s3, s3, 0xffe0
	s_sub_i32 s2, s2, s3
	s_bfe_i32 s3, s2, 0x80000
	s_bfe_u32 s3, s3, 0x3000c
	s_add_i32 s3, s2, s3
	s_lshl_b32 s13, s4, 3
	s_bfe_i32 s4, s3, 0x80000
	s_and_b32 s3, s3, 0xf8
	s_sub_i32 s2, s2, s3
	s_sext_i32_i16 s4, s4
	s_sext_i32_i8 s2, s2
	s_ashr_i32 s5, s46, 8
	s_lshr_b32 s4, s4, 3
	s_add_i32 s2, s13, s2
	s_ashr_i32 s12, s46, 6
	s_ashr_i32 s3, s2, 31
	s_bfe_i64 s[16:17], s[4:5], 0x100000
	v_and_b32_e32 v8, 0xc0, v8
	s_lshl_b32 s53, s12, 10
	s_lshl_b64 s[14:15], s[2:3], 18
	s_lshl_b64 s[16:17], s[16:17], 18
	v_sub_u32_e32 v5, v5, v8
	s_add_u32 s56, s6, s16
	v_lshlrev_b32_e32 v9, 5, v3
	v_ashrrev_i16_sdwa v5, v188, sext(v5) dst_sel:DWORD dst_unused:UNUSED_PAD src0_sel:DWORD src1_sel:BYTE_0
	v_lshlrev_b32_e32 v8, 1, v7
	v_lshrrev_b32_e32 v10, 2, v7
	s_addc_u32 s57, s7, s17
	s_add_i32 s3, s53, 0
	v_and_b32_e32 v9, 32, v9
	v_bfe_i32 v5, v5, 0, 16
	v_and_b32_e32 v8, 24, v8
	v_and_b32_e32 v10, 4, v10
	s_add_i32 m0, s3, 0x10000
	v_or3_b32 v8, v11, v10, v8
	v_add_lshl_u32 v9, v9, v5, 1
	global_load_lds_dwordx4 v128, s[56:57]
	s_add_i32 m0, s3, 0x12000
	v_lshl_add_u32 v152, v8, 10, v9
	s_add_u32 s36, s48, s14
	global_load_lds_dwordx4 v152, s[56:57]
	s_addc_u32 s37, s49, s15
	s_mov_b32 m0, s3
	s_add_i32 s60, s3, 0x2000
	v_lshl_add_u32 v150, v7, 10, v9
	global_load_lds_dwordx4 v148, s[36:37]
	s_mov_b32 m0, s60
	s_add_u32 s14, s56, 0x20000
	global_load_lds_dwordx4 v150, s[36:37]
	s_addc_u32 s15, s57, 0
	s_add_i32 m0, s3, 0x14000
	s_nop 0
	global_load_lds_dwordx4 v128, s[14:15]
	s_add_i32 m0, s3, 0x16000
	s_nop 0
	global_load_lds_dwordx4 v152, s[14:15]
	s_add_u32 s14, s36, 0x20000
	s_addc_u32 s15, s37, 0
	s_add_i32 s61, s3, 0x4000
	s_mov_b32 m0, s61
	s_add_i32 s62, s3, 0x6000
	global_load_lds_dwordx4 v148, s[14:15]
	s_mov_b32 m0, s62
	s_cmp_lg_u32 s5, 1
	global_load_lds_dwordx4 v150, s[14:15]
	s_setprio 1
	s_cbranch_scc1 .LBB0_325
	s_barrier
	s_setprio 0

; #define PG8_STAGE(bufoff, gbase, voff) do { _Pragma("unroll") for (int _i = 0; _i < 2; ++_i) \
;         __builtin_amdgcn_global_load_lds((const unsigned*)((const char*)(gbase) + (voff)[_i]), (PG8_LAS unsigned*)(lds + (bufoff) + ldsw + _i * 8192), 16, 0, 0); } while (0)
; #define PG8_BAR __builtin_amdgcn_s_barrier()
;     __host__ __device__ bool next(int i, Unit& u) const {
;         const long L = (long)i * G + c; if (L >= nwg) return false;
;         int wgid = (int)L; { const int q = nwg / NXCD, r = nwg % NXCD, xcd = wgid % NXCD, off = wgid / NXCD; wgid = (xcd < r ? xcd * (q + 1) : r * (q + 1) + (xcd - r) * q) + off; }
;         const int nig = WGM * nN, gid = wgid / nig, fm = gid * WGM, gsz = (nM - fm) < WGM ? (nM - fm) : WGM;
;         u.pm = fm + ((wgid % nig) % gsz); u.pn = (wgid % nig) / gsz; return true;
; template <class Epi, class Sched, bool STAMP = false>
; __device__ __forceinline__ void gemm_phase(PG8_LAS unsigned char* lds, const Gemm g, const Sched& S, const Epi& E, unsigned long long* stamps) {
;     ...
;     for (int i = 0; i < 2; ++i) { int R, C; stage_rc(tid * 16 + i * 8192, R, C); const int Rb = Epi::PERM ? ((R & ~31) + perm32(R & 31)) : R;
;         voffA[i] = (unsigned)(R * LD + C) * 2u; voffB[i] = (unsigned)(Rb * LD + C) * 2u; }
;     const size_t kstep = (size_t)(BK * 2);
;     const size_t hstep = (size_t)HALF * LD * 2;
;     const size_t tstep = 2 * hstep;
;     const unsigned ldsw = (unsigned)wid * 1024u;
;     const int aoff = lds_byte(wr * 64 + fr, fq * 8), boff = lds_byte(wc * 32 + fr, fq * 8);
;     ...
;     Unit cur, nxt; int ui = 0;
;     if (!S.next(0, cur)) return;
;     f32x4 acc[2][2][4][2];
; #pragma unroll
;     for (int a = 0; a < 2; ++a)
; #pragma unroll
;         for (int b = 0; b < 2; ++b)
; #pragma unroll
;             for (int m = 0; m < 4; ++m)
; #pragma unroll
;                 for (int n = 0; n < 2; ++n) acc[a][b][m][n] = (f32x4){0.f, 0.f, 0.f, 0.f};
;     bf16x8 At[4][2], B0[2][2], B1[2][2];
;     const char* cA = (const char*)g.A + (size_t)cur.pm * tstep; const char* cB = (const char*)g.Bt + (size_t)cur.pn * tstep;
;     S.a_ready(cur);
;     PG8_STAGE(PG8_SB(0, 0), cB, voffB); PG8_STAGE(PG8_SA(0, 0), cA, voffA); PG8_STAGE(PG8_SB(0, 1), cB + hstep, voffB); PG8_STAGE(PG8_SA(0, 1), cA + hstep, voffA);
;     if (wr == 1) PG8_BAR;
.LBB0_343:
	v_bfe_i32 v1, v6, 27, 1
	v_lshlrev_b32_e32 v3, 4, v6
	v_lshrrev_b32_e32 v1, 22, v1
	v_ashrrev_i32_e32 v0, 31, v6
	v_add_u32_e32 v1, v3, v1
	v_lshrrev_b32_e32 v0, 26, v0
	v_and_b32_e32 v1, 0xfffffc00, v1
	v_add_u32_e32 v0, v6, v0
	v_sub_u32_e32 v1, v3, v1
	v_ashrrev_i32_e32 v0, 6, v0
	v_lshrrev_b32_e32 v2, 4, v1
	v_bitop3_b32 v2, v2, v1, 32 bitop3:0x6c
	v_lshlrev_b32_e32 v1, 3, v0
	v_and_b32_e32 v4, -16, v1
	v_ashrrev_i32_e32 v1, 31, v2
	v_lshrrev_b32_e32 v1, 26, v1
	s_waitcnt lgkmcnt(0)
	v_add_u32_e32 v5, v2, v1
	v_ashrrev_i32_e32 v1, 6, v5
	v_and_b32_e32 v5, 0xc0, v5
	v_sub_u32_e32 v2, v2, v5
	v_lshlrev_b32_e32 v7, 5, v0
	v_ashrrev_i16_sdwa v2, v188, sext(v2) dst_sel:DWORD dst_unused:UNUSED_PAD src0_sel:DWORD src1_sel:BYTE_0
	v_and_b32_e32 v7, 32, v7
	v_bfe_i32 v2, v2, 0, 16
	v_add_u32_e32 v4, v1, v4
	v_and_b32_e32 v9, 3, v1
	s_mov_b32 s3, 0x1fffe0
	v_add_lshl_u32 v7, v7, v2, 1
	v_lshlrev_b32_e32 v5, 1, v4
	v_lshrrev_b32_e32 v8, 2, v4
	v_and_or_b32 v9, v4, s3, v9
	v_lshl_add_u32 v148, v4, 11, v7
	v_add_u32_e32 v4, 0x2000, v3
	v_ashrrev_i32_e32 v3, 31, v4
	v_lshrrev_b32_e32 v3, 22, v3
	v_and_b32_e32 v5, 24, v5
	v_and_b32_e32 v8, 4, v8
	v_add_u32_e32 v3, v4, v3
	v_or3_b32 v5, v9, v8, v5
	v_ashrrev_i32_e32 v3, 10, v3
	v_lshl_add_u32 v128, v5, 11, v7
	v_mul_i32_i24_e32 v5, 0x400, v3
	v_sub_u32_e32 v4, v4, v5
	v_lshrrev_b32_e32 v5, 4, v4
	v_bitop3_b32 v5, v5, v4, 32 bitop3:0x6c
	v_lshlrev_b32_e32 v4, 3, v3
	v_and_b32_e32 v7, -16, v4
	v_ashrrev_i32_e32 v4, 31, v5
	v_lshrrev_b32_e32 v4, 26, v4
	v_add_u32_e32 v8, v5, v4
	v_ashrrev_i32_e32 v4, 6, v8
	v_add_u32_e32 v7, v4, v7
	v_and_b32_e32 v11, 3, v4
	s_add_i32 s2, s4, s2
	v_and_or_b32 v11, v7, s3, v11
	s_ashr_i32 s3, s2, 31
	s_lshr_b32 s3, s3, 27
	s_add_i32 s3, s2, s3
	s_ashr_i32 s4, s3, 5
	s_and_b32 s3, s3, 0xffe0
	s_sub_i32 s2, s2, s3
	s_bfe_i32 s3, s2, 0x80000
	s_bfe_u32 s3, s3, 0x3000c
	s_add_i32 s3, s2, s3
	s_ashr_i32 s5, s13, 8
	s_mov_b32 s70, s13
	s_ashr_i32 s12, s13, 6
	s_lshl_b32 s13, s4, 3
	s_bfe_i32 s4, s3, 0x80000
	s_and_b32 s3, s3, 0xf8
	s_sub_i32 s2, s2, s3
	s_sext_i32_i16 s4, s4
	s_sext_i32_i8 s2, s2
	s_lshr_b32 s4, s4, 3
	s_add_i32 s2, s13, s2
	s_ashr_i32 s3, s2, 31
	s_bfe_i64 s[16:17], s[4:5], 0x100000
	v_and_b32_e32 v8, 0xc0, v8
	s_lshl_b32 s88, s12, 10
	s_lshl_b64 s[14:15], s[2:3], 19
	s_lshl_b64 s[16:17], s[16:17], 19
	v_sub_u32_e32 v5, v5, v8
	s_add_u32 s58, s24, s16
	v_lshlrev_b32_e32 v9, 5, v3
	v_ashrrev_i16_sdwa v5, v188, sext(v5) dst_sel:DWORD dst_unused:UNUSED_PAD src0_sel:DWORD src1_sel:BYTE_0
	v_lshlrev_b32_e32 v8, 1, v7
	v_lshrrev_b32_e32 v10, 2, v7
	s_addc_u32 s59, s25, s17
	s_add_i32 s89, s88, 0
	v_and_b32_e32 v9, 32, v9
	v_bfe_i32 v5, v5, 0, 16
	v_and_b32_e32 v8, 24, v8
	v_and_b32_e32 v10, 4, v10
	s_add_i32 m0, s89, 0x10000
	v_or3_b32 v8, v11, v10, v8
	v_add_lshl_u32 v9, v9, v5, 1
	global_load_lds_dwordx4 v128, s[58:59]
	s_add_i32 m0, s89, 0x12000
	v_lshl_add_u32 v152, v8, 11, v9
	s_add_u32 s56, s42, s14
	global_load_lds_dwordx4 v152, s[58:59]
	s_addc_u32 s57, s43, s15
	s_mov_b32 m0, s89
	s_add_i32 s96, s89, 0x2000
	v_lshl_add_u32 v150, v7, 11, v9
	global_load_lds_dwordx4 v148, s[56:57]
	s_mov_b32 m0, s96
	s_add_u32 s14, s58, 0x40000
	global_load_lds_dwordx4 v150, s[56:57]
	s_addc_u32 s15, s59, 0
	s_add_i32 m0, s89, 0x14000
	s_nop 0
	global_load_lds_dwordx4 v128, s[14:15]
	s_add_i32 m0, s89, 0x16000
	s_nop 0
	global_load_lds_dwordx4 v152, s[14:15]
	s_add_u32 s14, s56, 0x40000
	s_addc_u32 s15, s57, 0
	s_add_i32 s97, s89, 0x4000
	s_mov_b32 m0, s97
	s_add_i32 s64, s89, 0x6000
	global_load_lds_dwordx4 v148, s[14:15]
	s_mov_b32 m0, s64
	s_cmp_lg_u32 s5, 1
	global_load_lds_dwordx4 v150, s[14:15]
	s_setprio 1
	s_cbranch_scc1 .LBB0_345
	s_barrier
	s_setprio 0

; template <class Epi, class Sched, bool STAMP = false>
; __device__ __forceinline__ void gemm_phase(PG8_LAS unsigned char* lds, const Gemm g, const Sched& S, const Epi& E, unsigned long long* stamps) {
;     ...
;     for (int i = 0; i < 2; ++i) { int R, C; stage_rc(tid * 16 + i * 8192, R, C); const int Rb = Epi::PERM ? ((R & ~31) + perm32(R & 31)) : R;
;         voffA[i] = (unsigned)(R * LD + C) * 2u; voffB[i] = (unsigned)(Rb * LD + C) * 2u; }
;     const size_t kstep = (size_t)(BK * 2);
;     const size_t hstep = (size_t)HALF * LD * 2;
;     const size_t tstep = 2 * hstep;
;     const unsigned ldsw = (unsigned)wid * 1024u;
;     const int aoff = lds_byte(wr * 64 + fr, fq * 8), boff = lds_byte(wc * 32 + fr, fq * 8);
;     ...
;     Unit cur, nxt; int ui = 0;
;     if (!S.next(0, cur)) return;
;     f32x4 acc[2][2][4][2];
; #pragma unroll
;     for (int a = 0; a < 2; ++a)
; #pragma unroll
;         for (int b = 0; b < 2; ++b)
; #pragma unroll
;             for (int m = 0; m < 4; ++m)
; #pragma unroll
;                 for (int n = 0; n < 2; ++n) acc[a][b][m][n] = (f32x4){0.f, 0.f, 0.f, 0.f};
;     bf16x8 At[4][2], B0[2][2], B1[2][2];
;     const char* cA = (const char*)g.A + (size_t)cur.pm * tstep; const char* cB = (const char*)g.Bt + (size_t)cur.pn * tstep;
;     S.a_ready(cur);
;     PG8_STAGE(PG8_SB(0, 0), cB, voffB); PG8_STAGE(PG8_SA(0, 0), cA, voffA); PG8_STAGE(PG8_SB(0, 1), cB + hstep, voffB); PG8_STAGE(PG8_SA(0, 1), cA + hstep, voffA);
;     if (wr == 1) PG8_BAR;
; __device__ __forceinline__ void run_gate_sample_tasks(LAS unsigned char* lds, unsigned char* ws) {
;     const int t = bidx(); OneUnit S; S.valid = t < 192;
;     const bf16_t* A; const bf16_t* Bt; int ld, slot, u, sl;
;     if (t < 32)       { u = t >> 1; sl = t & 1; A = (const bf16_t*)(ws + OFF_B); Bt = (const bf16_t*)(ws + OFF_WOA); ld = 512; slot = sl; }
;     else if (t < 64)  { u = (t - 32) >> 1; sl = t & 1; A = (const bf16_t*)(ws + OFF_B + SLOT); Bt = (const bf16_t*)(ws + OFF_WOB); ld = 512; slot = 2 + sl; }
;     else if (t < 128) { u = (t - 64) >> 2; sl = t & 3; A = (const bf16_t*)(ws + OFF_XB); Bt = (const bf16_t*)(ws + OFF_WGA); ld = 1024; slot = 4 + sl; }
;     else              { u = ((t - 128) >> 2) & 15; sl = t & 3; A = (const bf16_t*)(ws + OFF_XB); Bt = (const bf16_t*)(ws + OFF_WGB); ld = 1024; slot = 8 + sl; }
;     S.pm = 64 + (u >> 2); S.pn = u & 3;
.LBB0_370:
	s_add_u32 s2, s91, 0xbb00000
	s_addc_u32 s3, s79, 0
	v_mov_b32_e32 v0, v184
	s_cmpk_gt_i32 s4, 0xbf
	s_nop 0
	v_readfirstlane_b32 s38, v0
	s_cbranch_scc1 .LBB0_378
	v_lshlrev_b32_e32 v1, 4, v0
	v_add_u32_e32 v2, 0x2000, v1
	v_ashrrev_i32_e32 v3, 31, v2
	v_lshrrev_b32_e32 v3, 22, v3
	v_add_u32_e32 v3, v2, v3
	v_ashrrev_i32_e32 v3, 10, v3
	v_mul_i32_i24_e32 v4, 0x400, v3
	v_sub_u32_e32 v2, v2, v4
	v_lshrrev_b32_e32 v4, 4, v2
	v_bitop3_b32 v2, v4, v2, 32 bitop3:0x6c
	v_ashrrev_i32_e32 v4, 31, v2
	v_lshrrev_b32_e32 v4, 26, v4
	v_add_u32_e32 v4, v2, v4
	v_lshlrev_b32_e32 v6, 3, v3
	s_waitcnt lgkmcnt(0)
	v_ashrrev_i32_e32 v5, 6, v4
	v_and_b32_e32 v6, 0x7ffffff0, v6
	v_and_b32_e32 v4, 0xc0, v4
	v_add_u32_e32 v5, v5, v6
	v_sub_u32_e32 v2, v2, v4
	v_mul_lo_u32 v5, v5, s13
	v_lshlrev_b32_e32 v3, 5, v3
	v_ashrrev_i16_sdwa v2, v188, sext(v2) dst_sel:DWORD dst_unused:UNUSED_PAD src0_sel:DWORD src1_sel:BYTE_0
	v_and_or_b32 v3, v3, 32, v5
	v_bfe_i32 v2, v2, 0, 16
	v_add_lshl_u32 v148, v3, v2, 1
	v_bfe_i32 v2, v0, 27, 1
	v_lshrrev_b32_e32 v2, 22, v2
	v_add_u32_e32 v2, v1, v2
	v_and_b32_e32 v2, 0xfffffc00, v2
	v_sub_u32_e32 v1, v1, v2
	v_lshrrev_b32_e32 v2, 4, v1
	v_ashrrev_i32_e32 v4, 31, v0
	v_bitop3_b32 v1, v2, v1, 32 bitop3:0x6c
	v_lshrrev_b32_e32 v4, 26, v4
	s_ashr_i32 s44, s12, 2
	s_ashr_i32 s14, s38, 6
	v_ashrrev_i32_e32 v2, 31, v1
	v_add_u32_e32 v4, v0, v4
	s_add_i32 s44, s44, 64
	s_and_b32 s39, s12, 3
	s_ashr_i32 s15, s38, 8
	s_lshl_b32 s45, s13, 8
	s_lshl_b32 s46, s14, 10
	s_lshl_b32 s4, s5, 9
	v_lshrrev_b32_e32 v2, 26, v2
	v_ashrrev_i32_e32 v4, 6, v4
	s_add_u32 s5, s24, s4
	v_add_u32_e32 v2, v1, v2
	v_lshlrev_b32_e32 v5, 3, v4
	s_addc_u32 s6, s25, 0
	v_ashrrev_i32_e32 v3, 6, v2
	v_and_b32_e32 v5, 0x7ffffff0, v5
	s_add_u32 s7, s42, s4
	v_add_u32_e32 v3, v3, v5
	s_addc_u32 s12, s43, 0
	s_lshl_b32 s4, s13, 9
	v_mul_lo_u32 v3, v3, s13
	s_ashr_i32 s13, s44, 31
	v_and_b32_e32 v2, 0xc0, v2
	s_mul_hi_u32 s16, s4, s44
	s_mul_i32 s13, s4, s13
	v_sub_u32_e32 v1, v1, v2
	s_add_i32 s16, s16, s13
	s_mul_i32 s13, s4, s44
	s_mul_i32 s4, s4, s39
	v_lshlrev_b32_e32 v4, 5, v4
	v_ashrrev_i16_sdwa v1, v188, sext(v1) dst_sel:DWORD dst_unused:UNUSED_PAD src0_sel:DWORD src1_sel:BYTE_0
	s_add_u32 s4, s5, s4
	v_and_or_b32 v3, v4, 32, v3
	v_bfe_i32 v1, v1, 0, 16
	s_addc_u32 s5, s6, 0
	s_add_i32 s42, s46, 0
	v_add_lshl_u32 v128, v3, v1, 1
	s_add_i32 m0, s42, 0x10000
	s_nop 0
	global_load_lds_dwordx4 v128, s[4:5]
	s_add_i32 m0, s42, 0x12000
	s_add_u32 s6, s7, s13
	global_load_lds_dwordx4 v148, s[4:5]
	s_addc_u32 s7, s12, s16
	s_mov_b32 m0, s42
	s_add_i32 s43, s42, 0x2000
	global_load_lds_dwordx4 v128, s[6:7]
	s_mov_b32 m0, s43
	s_add_u32 s20, s4, s45
	global_load_lds_dwordx4 v148, s[6:7]
	s_addc_u32 s21, s5, 0
	s_add_i32 m0, s42, 0x14000
	s_nop 0
	global_load_lds_dwordx4 v128, s[20:21]
	s_add_i32 m0, s42, 0x16000
	s_add_u32 s12, s6, s45
	s_addc_u32 s13, s7, 0
	s_add_i32 s47, s42, 0x4000
	global_load_lds_dwordx4 v148, s[20:21]
	s_mov_b32 m0, s47
	s_add_i32 s48, s42, 0x6000
	global_load_lds_dwordx4 v128, s[12:13]
	s_mov_b32 m0, s48
	s_cmp_lg_u32 s15, 1
	global_load_lds_dwordx4 v148, s[12:13]
	s_setprio 1
	s_cbranch_scc1 .LBB0_373
	s_barrier
	s_setprio 0

; #define PG8_STAGE(bufoff, gbase, voff) do { _Pragma("unroll") for (int _i = 0; _i < 2; ++_i) \
;         __builtin_amdgcn_global_load_lds((const unsigned*)((const char*)(gbase) + (voff)[_i]), (PG8_LAS unsigned*)(lds + (bufoff) + ldsw + _i * 8192), 16, 0, 0); } while (0)
; #define PG8_BAR __builtin_amdgcn_s_barrier()
;     __host__ __device__ bool next(int i, Unit& u) const {
;         const long L = (long)i * G + c; if (L >= nwg) return false;
;         int wgid = (int)L; { const int q = nwg / NXCD, r = nwg % NXCD, xcd = wgid % NXCD, off = wgid / NXCD; wgid = (xcd < r ? xcd * (q + 1) : r * (q + 1) + (xcd - r) * q) + off; }
;         const int nig = WGM * nN, gid = wgid / nig, fm = gid * WGM, gsz = (nM - fm) < WGM ? (nM - fm) : WGM;
;         u.pm = fm + ((wgid % nig) % gsz); u.pn = (wgid % nig) / gsz; return true;
; template <class Epi, class Sched, bool STAMP = false>
; __device__ __forceinline__ void gemm_phase(PG8_LAS unsigned char* lds, const Gemm g, const Sched& S, const Epi& E, unsigned long long* stamps) {
;     ...
;     for (int i = 0; i < 2; ++i) { int R, C; stage_rc(tid * 16 + i * 8192, R, C); const int Rb = Epi::PERM ? ((R & ~31) + perm32(R & 31)) : R;
;         voffA[i] = (unsigned)(R * LD + C) * 2u; voffB[i] = (unsigned)(Rb * LD + C) * 2u; }
;     const size_t kstep = (size_t)(BK * 2);
;     const size_t hstep = (size_t)HALF * LD * 2;
;     const size_t tstep = 2 * hstep;
;     const unsigned ldsw = (unsigned)wid * 1024u;
;     const int aoff = lds_byte(wr * 64 + fr, fq * 8), boff = lds_byte(wc * 32 + fr, fq * 8);
;     ...
;     Unit cur, nxt; int ui = 0;
;     if (!S.next(0, cur)) return;
;     f32x4 acc[2][2][4][2];
; #pragma unroll
;     for (int a = 0; a < 2; ++a)
; #pragma unroll
;         for (int b = 0; b < 2; ++b)
; #pragma unroll
;             for (int m = 0; m < 4; ++m)
; #pragma unroll
;                 for (int n = 0; n < 2; ++n) acc[a][b][m][n] = (f32x4){0.f, 0.f, 0.f, 0.f};
;     bf16x8 At[4][2], B0[2][2], B1[2][2];
;     const char* cA = (const char*)g.A + (size_t)cur.pm * tstep; const char* cB = (const char*)g.Bt + (size_t)cur.pn * tstep;
;     S.a_ready(cur);
;     PG8_STAGE(PG8_SB(0, 0), cB, voffB); PG8_STAGE(PG8_SA(0, 0), cA, voffA); PG8_STAGE(PG8_SB(0, 1), cB + hstep, voffB); PG8_STAGE(PG8_SA(0, 1), cA + hstep, voffA);
;     if (wr == 1) PG8_BAR;
.LBB0_487:
	s_andn2_b64 vcc, exec, s[0:1]
	s_cbranch_vccnz .LBB0_547
	s_mov_b32 s2, s86
	s_mov_b32 s3, s87
	s_mov_b32 s10, s90
	v_mov_b32_e32 v14, v184
	s_cmpk_gt_i32 s10, 0x21f
	v_readfirstlane_b32 s36, v14
	s_cbranch_scc1 .LBB0_500
	v_lshlrev_b32_e32 v0, 4, v14
	v_add_u32_e32 v1, 0x2000, v0
	v_ashrrev_i32_e32 v2, 31, v1
	v_lshrrev_b32_e32 v2, 22, v2
	v_add_u32_e32 v2, v1, v2
	v_ashrrev_i32_e32 v8, 10, v2
	v_mul_i32_i24_e32 v2, 0x400, v8
	v_sub_u32_e32 v1, v1, v2
	v_lshrrev_b32_e32 v2, 4, v1
	v_bitop3_b32 v1, v2, v1, 32 bitop3:0x6c
	v_ashrrev_i32_e32 v2, 31, v1
	v_lshrrev_b32_e32 v2, 26, v2
	v_add_u32_e32 v2, v1, v2
	v_lshlrev_b32_e32 v3, 3, v8
	v_ashrrev_i32_e32 v9, 6, v2
	v_and_b32_e32 v3, -16, v3
	v_add_u32_e32 v3, v9, v3
	v_and_b32_e32 v4, 3, v9
	s_mov_b32 s0, 0x1fffe0
	s_waitcnt lgkmcnt(0)
	v_lshrrev_b32_e32 v5, 2, v3
	v_lshlrev_b32_e32 v6, 1, v3
	v_and_b32_e32 v2, 0xc0, v2
	v_and_or_b32 v4, v3, s0, v4
	v_and_b32_e32 v5, 4, v5
	v_and_b32_e32 v6, 24, v6
	v_sub_u32_e32 v1, v1, v2
	v_or3_b32 v4, v4, v5, v6
	v_lshlrev_b32_e32 v5, 5, v8
	v_ashrrev_i16_sdwa v1, v188, sext(v1) dst_sel:DWORD dst_unused:UNUSED_PAD src0_sel:DWORD src1_sel:BYTE_0
	v_and_b32_e32 v5, 32, v5
	v_bfe_i32 v10, v1, 0, 16
	v_add_lshl_u32 v1, v5, v10, 1
	v_lshl_add_u32 v148, v4, 11, v1
	v_lshl_add_u32 v150, v3, 11, v1
	v_bfe_i32 v1, v14, 27, 1
	v_lshrrev_b32_e32 v1, 22, v1
	v_add_u32_e32 v1, v0, v1
	v_and_b32_e32 v1, 0xfffffc00, v1
	v_sub_u32_e32 v0, v0, v1
	v_lshrrev_b32_e32 v1, 4, v0
	v_ashrrev_i32_e32 v2, 31, v14
	v_bitop3_b32 v0, v1, v0, 32 bitop3:0x6c
	v_lshrrev_b32_e32 v2, 26, v2
	v_ashrrev_i32_e32 v1, 31, v0
	v_add_u32_e32 v2, v14, v2
	s_add_u32 s37, s2, 0x2200000
	v_lshrrev_b32_e32 v1, 26, v1
	v_ashrrev_i32_e32 v12, 6, v2
	s_addc_u32 s40, s3, 0
	v_add_u32_e32 v1, v0, v1
	v_lshlrev_b32_e32 v2, 3, v12
	s_add_u32 s41, s2, 0x400000
	v_ashrrev_i32_e32 v11, 6, v1
	v_and_b32_e32 v2, -16, v2
	s_addc_u32 s42, s3, 0
	v_add_u32_e32 v2, v11, v2
	v_and_b32_e32 v3, 3, v11
	s_ashr_i32 s44, s10, 31
	v_and_or_b32 v3, v2, s0, v3
	s_lshr_b32 s0, s44, 29
	s_add_i32 s0, s10, s0
	s_ashr_i32 s4, s36, 6
	s_ashr_i32 s1, s0, 3
	s_and_b32 s0, s0, -8
	s_ashr_i32 s5, s36, 8
	s_lshl_b32 s43, s4, 10
	s_sub_i32 s0, s10, s0
	s_cmp_lt_i32 s0, 0
	s_movk_i32 s6, 0x45
	s_cselect_b32 s6, s6, 0x44
	s_mul_i32 s0, s6, s0
	s_add_i32 s0, s0, s1
	s_ashr_i32 s1, s0, 31
	s_lshr_b32 s1, s1, 26
	v_lshrrev_b32_e32 v4, 2, v2
	v_lshlrev_b32_e32 v5, 1, v2
	v_and_b32_e32 v1, 0xc0, v1
	s_add_i32 s1, s0, s1
	v_and_b32_e32 v4, 4, v4
	v_and_b32_e32 v5, 24, v5
	v_sub_u32_e32 v0, v0, v1
	s_ashr_i32 s6, s1, 6
	v_or3_b32 v3, v3, v4, v5
	v_lshlrev_b32_e32 v4, 5, v12
	v_ashrrev_i16_sdwa v0, v188, sext(v0) dst_sel:DWORD dst_unused:UNUSED_PAD src0_sel:DWORD src1_sel:BYTE_0
	s_lshl_b32 s6, s6, 3
	v_and_b32_e32 v4, 32, v4
	v_bfe_i32 v13, v0, 0, 16
	s_sub_i32 s7, 0x44, s6
	v_add_lshl_u32 v0, v4, v13, 1
	s_min_u32 s7, s7, 8
	s_andn2_b32 s1, s1, 63
	v_lshl_add_u32 v128, v3, 11, v0
	s_sub_i32 s12, s0, s1
	v_cvt_f32_ubyte0_e32 v3, s7
	v_cvt_f32_i32_e32 v1, s12
	v_rcp_iflag_f32_e32 v4, v3
	v_lshl_add_u32 v152, v2, 11, v0
	s_ashr_i32 s0, s12, 30
	s_or_b32 s13, s0, 1
	v_mul_f32_e32 v0, v1, v4
	v_trunc_f32_e32 v0, v0
	v_fma_f32 v1, -v0, v3, v1
	v_cvt_i32_f32_e32 v0, v0
	v_cmp_ge_f32_e64 s[0:1], |v1|, v3
	s_and_b64 s[0:1], s[0:1], exec
	s_cselect_b32 s0, s13, 0
	v_readfirstlane_b32 s1, v0
	s_add_i32 s0, s1, s0
	s_mul_i32 s1, s0, s7
	s_sub_i32 s1, s12, s1
	s_sext_i32_i8 s1, s1
	s_add_i32 s22, s6, s1
	s_ashr_i32 s23, s22, 31
	s_bfe_i64 s[12:13], s[0:1], 0x80000
	s_lshl_b64 s[6:7], s[22:23], 19
	s_lshl_b64 s[12:13], s[12:13], 19
	s_add_u32 s26, s41, s12
	s_addc_u32 s27, s42, s13
	s_add_i32 s23, s43, 0
	s_add_i32 m0, s23, 0x10000
	v_mov_b32_e32 v149, v129
	global_load_lds_dwordx4 v128, s[26:27]
	s_add_i32 m0, s23, 0x12000
	s_add_u32 s24, s37, s6
	global_load_lds_dwordx4 v148, s[26:27]
	s_addc_u32 s25, s40, s7
	s_mov_b32 m0, s23
	s_add_i32 s45, s23, 0x2000
	global_load_lds_dwordx4 v152, s[24:25]
	s_mov_b32 m0, s45
	s_add_u32 s6, s26, 0x40000
	global_load_lds_dwordx4 v150, s[24:25]
	s_addc_u32 s7, s27, 0
	s_add_i32 m0, s23, 0x14000
	v_mov_b32_e32 v153, v129
	global_load_lds_dwordx4 v128, s[6:7]
	s_add_i32 m0, s23, 0x16000
	v_mov_b32_e32 v151, v129
	global_load_lds_dwordx4 v148, s[6:7]
	s_add_u32 s6, s24, 0x40000
	s_addc_u32 s7, s25, 0
	s_add_i32 s46, s23, 0x4000
	s_mov_b32 m0, s46
	s_add_i32 s47, s23, 0x6000
	global_load_lds_dwordx4 v152, s[6:7]
	s_mov_b32 m0, s47
	s_mov_b32 s63, s65
	global_load_lds_dwordx4 v150, s[6:7]
	v_lshl_add_u64 v[6:7], s[26:27], 0, v[128:129]
	v_lshl_add_u64 v[4:5], s[26:27], 0, v[148:149]
	v_lshl_add_u64 v[2:3], s[24:25], 0, v[152:153]
	s_cmp_lg_u32 s5, 1
	v_lshl_add_u64 v[0:1], s[24:25], 0, v[150:151]
	s_setprio 1
	s_cbranch_scc1 .LBB0_491
	s_barrier
	s_setprio 0

; #define PG8_STAGE(bufoff, gbase, voff) do { _Pragma("unroll") for (int _i = 0; _i < 2; ++_i) \
;         __builtin_amdgcn_global_load_lds((const unsigned*)((const char*)(gbase) + (voff)[_i]), (PG8_LAS unsigned*)(lds + (bufoff) + ldsw + _i * 8192), 16, 0, 0); } while (0)
; template <class Epi, class Sched, bool STAMP = false>
; __device__ __forceinline__ void gemm_phase(PG8_LAS unsigned char* lds, const Gemm g, const Sched& S, const Epi& E, unsigned long long* stamps) {
;     ...
;     for (int i = 0; i < 2; ++i) { int R, C; stage_rc(tid * 16 + i * 8192, R, C); const int Rb = Epi::PERM ? ((R & ~31) + perm32(R & 31)) : R;
;         voffA[i] = (unsigned)(R * LD + C) * 2u; voffB[i] = (unsigned)(Rb * LD + C) * 2u; }
;     const size_t kstep = (size_t)(BK * 2);
;     const size_t hstep = (size_t)HALF * LD * 2;
;     const size_t tstep = 2 * hstep;
;     const unsigned ldsw = (unsigned)wid * 1024u;
;     const int aoff = lds_byte(wr * 64 + fr, fq * 8), boff = lds_byte(wc * 32 + fr, fq * 8);
;     ...
;     Unit cur, nxt; int ui = 0;
;     if (!S.next(0, cur)) return;
;     f32x4 acc[2][2][4][2];
; #pragma unroll
;     for (int a = 0; a < 2; ++a)
; #pragma unroll
;         for (int b = 0; b < 2; ++b)
; #pragma unroll
;             for (int m = 0; m < 4; ++m)
; #pragma unroll
;                 for (int n = 0; n < 2; ++n) acc[a][b][m][n] = (f32x4){0.f, 0.f, 0.f, 0.f};
;     bf16x8 At[4][2], B0[2][2], B1[2][2];
;     const char* cA = (const char*)g.A + (size_t)cur.pm * tstep; const char* cB = (const char*)g.Bt + (size_t)cur.pn * tstep;
;     S.a_ready(cur);
;     PG8_STAGE(PG8_SB(0, 0), cB, voffB); PG8_STAGE(PG8_SA(0, 0), cA, voffA); PG8_STAGE(PG8_SB(0, 1), cB + hstep, voffB); PG8_STAGE(PG8_SA(0, 1), cA + hstep, voffA);
;     if (wr == 1) PG8_BAR;
; __device__ __forceinline__ void run_ffn_down(LAS unsigned char* lds, const bf16_t* HID, const bf16_t* WDN, const EpiResid& E, float* PART) {
;     { pg8::StaticOrder S; S.init(T_P, 1024, (int)gridDim.x, bidx());
;       pg8::Gemm g; g.A = HID; g.Bt = WDN; g.M = T_P; g.N = 1024; g.K = 4096; g.ld = 4096;
;       pg8::gemm_phase<EpiResid, pg8::StaticOrder, false>(lds, g, S, E, nullptr); }
;     { const int t = bidx(); OneUnit S; S.valid = t < 128; const int sl = t & 7, u = (t >> 3) & 15; S.pm = 64 + (u >> 2); S.pn = u & 3;
;       pg8::Gemm g; g.A = HID + sl * 512; g.Bt = WDN + sl * 512; g.M = T_ALL; g.N = 1024; g.K = 512; g.ld = 4096;
.LBB0_1171:
	s_add_u32 s45, s10, 0x5500000
	s_addc_u32 s46, s42, 0
	s_add_u32 s47, s10, 0x1800000
	s_addc_u32 s48, s42, 0
	s_andn2_b64 vcc, exec, s[0:1]
	s_cbranch_vccnz .LBB0_1203
	v_ashrrev_i32_e32 v1, 31, v9
	v_lshrrev_b32_e32 v1, 26, v1
	v_add_u32_e32 v1, v9, v1
	v_ashrrev_i32_e32 v8, 6, v1
	v_bfe_i32 v1, v9, 27, 1
	v_lshlrev_b32_e32 v0, 4, v9
	v_lshrrev_b32_e32 v1, 22, v1
	v_add_u32_e32 v1, v0, v1
	v_and_b32_e32 v1, 0xfffffc00, v1
	v_sub_u32_e32 v1, v0, v1
	v_lshrrev_b32_e32 v2, 4, v1
	v_bitop3_b32 v1, v2, v1, 32 bitop3:0x6c
	v_ashrrev_i32_e32 v3, 31, v1
	v_lshrrev_b32_e32 v3, 26, v3
	v_add_u32_e32 v3, v1, v3
	v_lshlrev_b32_e32 v2, 3, v8
	v_ashrrev_i32_e32 v10, 6, v3
	v_and_b32_e32 v3, 0xc0, v3
	v_and_b32_e32 v2, 0x7fff0, v2
	v_lshlrev_b32_e32 v4, 5, v8
	v_sub_u32_e32 v1, v1, v3
	v_add_u32_e32 v2, v10, v2
	v_and_b32_e32 v11, 32, v4
	v_ashrrev_i16_sdwa v1, v188, sext(v1) dst_sel:DWORD dst_unused:UNUSED_PAD src0_sel:DWORD src1_sel:BYTE_0
	s_waitcnt lgkmcnt(0)
	v_bfe_i32 v12, v1, 0, 16
	v_lshl_or_b32 v1, v2, 12, v11
	v_add_u32_e32 v0, 0x2000, v0
	v_add_lshl_u32 v128, v1, v12, 1
	v_ashrrev_i32_e32 v1, 31, v0
	v_lshrrev_b32_e32 v1, 22, v1
	v_add_u32_e32 v1, v0, v1
	v_ashrrev_i32_e32 v13, 10, v1
	v_mul_i32_i24_e32 v1, 0x400, v13
	v_sub_u32_e32 v0, v0, v1
	v_lshrrev_b32_e32 v1, 4, v0
	v_bitop3_b32 v0, v1, v0, 32 bitop3:0x6c
	v_ashrrev_i32_e32 v2, 31, v0
	v_lshrrev_b32_e32 v2, 26, v2
	s_ashr_i32 s5, s44, 6
	s_ashr_i32 s23, s22, 31
	s_ashr_i32 s25, s24, 31
	s_ashr_i32 s4, s44, 8
	v_add_u32_e32 v2, v0, v2
	s_lshl_b32 s49, s5, 10
	s_lshl_b64 s[0:1], s[22:23], 21
	s_lshl_b64 s[2:3], s[24:25], 21
	v_lshlrev_b32_e32 v1, 3, v13
	v_ashrrev_i32_e32 v14, 6, v2
	v_and_b32_e32 v2, 0xc0, v2
	s_add_u32 s30, s47, s2
	v_and_b32_e32 v1, 0x7fff0, v1
	v_lshlrev_b32_e32 v3, 5, v13
	v_sub_u32_e32 v0, v0, v2
	s_addc_u32 s31, s48, s3
	s_add_i32 s25, s49, 0
	v_add_u32_e32 v1, v14, v1
	v_and_b32_e32 v15, 32, v3
	v_ashrrev_i16_sdwa v0, v188, sext(v0) dst_sel:DWORD dst_unused:UNUSED_PAD src0_sel:DWORD src1_sel:BYTE_0
	s_add_i32 m0, s25, 0x10000
	v_bfe_i32 v16, v0, 0, 16
	v_lshl_or_b32 v0, v1, 12, v15
	global_load_lds_dwordx4 v128, s[30:31]
	s_add_i32 m0, s25, 0x12000
	v_add_lshl_u32 v148, v0, v16, 1
	s_add_u32 s26, s45, s0
	global_load_lds_dwordx4 v148, s[30:31]
	s_addc_u32 s27, s46, s1
	s_mov_b32 m0, s25
	s_add_i32 s53, s25, 0x2000
	global_load_lds_dwordx4 v128, s[26:27]
	s_mov_b32 m0, s53
	s_add_u32 s0, s30, 0x100000
	global_load_lds_dwordx4 v148, s[26:27]
	s_addc_u32 s1, s31, 0
	s_add_i32 m0, s25, 0x14000
	v_mov_b32_e32 v149, v129
	global_load_lds_dwordx4 v128, s[0:1]
	s_add_i32 m0, s25, 0x16000
	v_lshl_add_u64 v[6:7], s[30:31], 0, v[128:129]
	global_load_lds_dwordx4 v148, s[0:1]
	s_add_u32 s0, s26, 0x100000
	s_addc_u32 s1, s27, 0
	s_add_i32 s56, s25, 0x4000
	s_mov_b32 m0, s56
	s_add_i32 s57, s25, 0x6000
	global_load_lds_dwordx4 v128, s[0:1]
	s_mov_b32 m0, s57
	v_lshl_add_u64 v[4:5], s[30:31], 0, v[148:149]
	global_load_lds_dwordx4 v148, s[0:1]
	v_lshl_add_u64 v[2:3], s[26:27], 0, v[128:129]
	s_cmp_lg_u32 s4, 1
	v_lshl_add_u64 v[0:1], s[26:27], 0, v[148:149]
	s_setprio 1
	s_cbranch_scc1 .LBB0_1174
	s_barrier
	s_setprio 0

; #define PG8_STAGE(bufoff, gbase, voff) do { _Pragma("unroll") for (int _i = 0; _i < 2; ++_i) \
;         __builtin_amdgcn_global_load_lds((const unsigned*)((const char*)(gbase) + (voff)[_i]), (PG8_LAS unsigned*)(lds + (bufoff) + ldsw + _i * 8192), 16, 0, 0); } while (0)
; #define PG8_BAR __builtin_amdgcn_s_barrier()
; template <class Epi, class Sched, bool STAMP = false>
; __device__ __forceinline__ void gemm_phase(PG8_LAS unsigned char* lds, const Gemm g, const Sched& S, const Epi& E, unsigned long long* stamps) {
;     ...
;     for (int i = 0; i < 2; ++i) { int R, C; stage_rc(tid * 16 + i * 8192, R, C); const int Rb = Epi::PERM ? ((R & ~31) + perm32(R & 31)) : R;
;         voffA[i] = (unsigned)(R * LD + C) * 2u; voffB[i] = (unsigned)(Rb * LD + C) * 2u; }
;     const size_t kstep = (size_t)(BK * 2);
;     const size_t hstep = (size_t)HALF * LD * 2;
;     const size_t tstep = 2 * hstep;
;     const unsigned ldsw = (unsigned)wid * 1024u;
;     const int aoff = lds_byte(wr * 64 + fr, fq * 8), boff = lds_byte(wc * 32 + fr, fq * 8);
;     ...
;     Unit cur, nxt; int ui = 0;
;     if (!S.next(0, cur)) return;
;     f32x4 acc[2][2][4][2];
; #pragma unroll
;     for (int a = 0; a < 2; ++a)
; #pragma unroll
;         for (int b = 0; b < 2; ++b)
; #pragma unroll
;             for (int m = 0; m < 4; ++m)
; #pragma unroll
;                 for (int n = 0; n < 2; ++n) acc[a][b][m][n] = (f32x4){0.f, 0.f, 0.f, 0.f};
;     bf16x8 At[4][2], B0[2][2], B1[2][2];
;     const char* cA = (const char*)g.A + (size_t)cur.pm * tstep; const char* cB = (const char*)g.Bt + (size_t)cur.pn * tstep;
;     S.a_ready(cur);
;     PG8_STAGE(PG8_SB(0, 0), cB, voffB); PG8_STAGE(PG8_SA(0, 0), cA, voffA); PG8_STAGE(PG8_SB(0, 1), cB + hstep, voffB); PG8_STAGE(PG8_SA(0, 1), cA + hstep, voffA);
;     if (wr == 1) PG8_BAR;
; __device__ __forceinline__ void run_ffn_down(LAS unsigned char* lds, const bf16_t* HID, const bf16_t* WDN, const EpiResid& E, float* PART) {
;     ...
;     { const int t = bidx(); OneUnit S; S.valid = t < 128; const int sl = t & 7, u = (t >> 3) & 15; S.pm = 64 + (u >> 2); S.pn = u & 3;
;       pg8::Gemm g; g.A = HID + sl * 512; g.Bt = WDN + sl * 512; g.M = T_ALL; g.N = 1024; g.K = 512; g.ld = 4096;
;       EpiPartial EA; EA.PART = PART + (size_t)sl * 1024 * 1024; EA.ldp = 1024;
;       pg8::gemm_phase<EpiPartial, OneUnit, false>(lds, g, S, EA, nullptr); }
.LBB0_1203:
	s_mov_b32 s4, s90
	s_waitcnt lgkmcnt(0)
	v_mov_b32_e32 v12, v184
	s_cmpk_gt_i32 s4, 0x7f
	s_nop 0
	v_readfirstlane_b32 s22, v12
	s_cbranch_scc1 .LBB0_1211
	v_lshlrev_b32_e32 v0, 4, v12
	v_add_u32_e32 v1, 0x2000, v0
	v_ashrrev_i32_e32 v2, 31, v1
	v_lshrrev_b32_e32 v2, 22, v2
	v_add_u32_e32 v2, v1, v2
	v_ashrrev_i32_e32 v8, 10, v2
	v_mul_i32_i24_e32 v2, 0x400, v8
	v_sub_u32_e32 v1, v1, v2
	v_lshrrev_b32_e32 v2, 4, v1
	v_bitop3_b32 v1, v2, v1, 32 bitop3:0x6c
	v_ashrrev_i32_e32 v2, 31, v1
	v_lshrrev_b32_e32 v2, 26, v2
	v_add_u32_e32 v2, v1, v2
	v_ashrrev_i32_e32 v9, 6, v2
	v_and_b32_e32 v2, 0xc0, v2
	v_sub_u32_e32 v1, v1, v2
	v_ashrrev_i16_sdwa v1, v188, sext(v1) dst_sel:DWORD dst_unused:UNUSED_PAD src0_sel:DWORD src1_sel:BYTE_0
	v_bfe_i32 v11, v1, 0, 16
	v_bfe_i32 v1, v12, 27, 1
	v_lshrrev_b32_e32 v1, 22, v1
	v_add_u32_e32 v1, v0, v1
	v_and_b32_e32 v1, 0xfffffc00, v1
	v_sub_u32_e32 v0, v0, v1
	v_lshrrev_b32_e32 v1, 4, v0
	s_and_b32 s25, s4, 7
	s_bfe_u32 s0, s4, 0x20005
	s_ashr_i32 s6, s22, 6
	v_bitop3_b32 v0, v1, v0, 32 bitop3:0x6c
	v_ashrrev_i32_e32 v2, 31, v12
	s_or_b32 s24, s0, 64
	s_bfe_u32 s23, s4, 0x20003
	s_ashr_i32 s7, s22, 8
	s_lshl_b32 s26, s6, 10
	s_lshl_b32 s5, s25, 10
	v_lshlrev_b32_e32 v3, 3, v8
	v_ashrrev_i32_e32 v1, 31, v0
	v_lshrrev_b32_e32 v2, 26, v2
	s_add_u32 s0, s47, s5
	v_and_b32_e32 v3, 0x7fff0, v3
	v_lshlrev_b32_e32 v4, 5, v8
	v_lshrrev_b32_e32 v1, 26, v1
	v_add_u32_e32 v2, v12, v2
	s_addc_u32 s1, s48, 0
	v_add_u32_e32 v3, v9, v3
	v_and_b32_e32 v10, 32, v4
	v_add_u32_e32 v1, v0, v1
	v_ashrrev_i32_e32 v14, 6, v2
	s_add_u32 s2, s45, s5
	v_lshl_or_b32 v3, v3, 12, v10
	v_ashrrev_i32_e32 v13, 6, v1
	v_lshlrev_b32_e32 v2, 3, v14
	v_and_b32_e32 v1, 0xc0, v1
	s_addc_u32 s3, s46, 0
	v_add_lshl_u32 v148, v3, v11, 1
	v_and_b32_e32 v2, 0x7fff0, v2
	v_lshlrev_b32_e32 v3, 5, v14
	v_sub_u32_e32 v0, v0, v1
	s_lshl_b32 s12, s24, 21
	s_lshl_b32 s13, s23, 21
	v_add_u32_e32 v2, v13, v2
	v_and_b32_e32 v15, 32, v3
	v_ashrrev_i16_sdwa v0, v188, sext(v0) dst_sel:DWORD dst_unused:UNUSED_PAD src0_sel:DWORD src1_sel:BYTE_0
	s_add_u32 s0, s0, s13
	v_lshl_or_b32 v2, v2, 12, v15
	v_bfe_i32 v16, v0, 0, 16
	s_addc_u32 s1, s1, 0
	s_add_i32 s27, s26, 0
	v_add_lshl_u32 v128, v2, v16, 1
	s_add_i32 m0, s27, 0x10000
	v_mov_b32_e32 v149, v129
	global_load_lds_dwordx4 v128, s[0:1]
	s_add_i32 m0, s27, 0x12000
	s_add_u32 s2, s2, s12
	global_load_lds_dwordx4 v148, s[0:1]
	s_addc_u32 s3, s3, 0
	s_mov_b32 m0, s27
	s_add_i32 s30, s27, 0x2000
	global_load_lds_dwordx4 v128, s[2:3]
	s_mov_b32 m0, s30
	s_add_u32 s12, s0, 0x100000
	global_load_lds_dwordx4 v148, s[2:3]
	s_addc_u32 s13, s1, 0
	s_add_i32 m0, s27, 0x14000
	v_lshl_add_u64 v[6:7], s[0:1], 0, v[128:129]
	global_load_lds_dwordx4 v128, s[12:13]
	s_add_i32 m0, s27, 0x16000
	v_lshl_add_u64 v[4:5], s[0:1], 0, v[148:149]
	global_load_lds_dwordx4 v148, s[12:13]
	s_add_u32 s12, s2, 0x100000
	s_addc_u32 s13, s3, 0
	s_add_i32 s31, s27, 0x4000
	s_mov_b32 m0, s31
	s_add_i32 s34, s27, 0x6000
	global_load_lds_dwordx4 v128, s[12:13]
	s_mov_b32 m0, s34
	v_lshl_add_u64 v[2:3], s[2:3], 0, v[128:129]
	global_load_lds_dwordx4 v148, s[12:13]
	s_cmp_lg_u32 s7, 1
	v_lshl_add_u64 v[0:1], s[2:3], 0, v[148:149]
	s_setprio 1
	s_cbranch_scc1 .LBB0_1206
	s_barrier
	s_setprio 0

; #define PG8_STAGE(bufoff, gbase, voff) do { _Pragma("unroll") for (int _i = 0; _i < 2; ++_i) \
;         __builtin_amdgcn_global_load_lds((const unsigned*)((const char*)(gbase) + (voff)[_i]), (PG8_LAS unsigned*)(lds + (bufoff) + ldsw + _i * 8192), 16, 0, 0); } while (0)
; #define PG8_BAR __builtin_amdgcn_s_barrier()
;     __host__ __device__ bool next(int i, Unit& u) const {
;         const long L = (long)i * G + c; if (L >= nwg) return false;
;         int wgid = (int)L; { const int q = nwg / NXCD, r = nwg % NXCD, xcd = wgid % NXCD, off = wgid / NXCD; wgid = (xcd < r ? xcd * (q + 1) : r * (q + 1) + (xcd - r) * q) + off; }
;         const int nig = WGM * nN, gid = wgid / nig, fm = gid * WGM, gsz = (nM - fm) < WGM ? (nM - fm) : WGM;
;         u.pm = fm + ((wgid % nig) % gsz); u.pn = (wgid % nig) / gsz; return true;
; template <class Epi, class Sched, bool STAMP = false>
; __device__ __forceinline__ void gemm_phase(PG8_LAS unsigned char* lds, const Gemm g, const Sched& S, const Epi& E, unsigned long long* stamps) {
;     ...
;     for (int i = 0; i < 2; ++i) { int R, C; stage_rc(tid * 16 + i * 8192, R, C); const int Rb = Epi::PERM ? ((R & ~31) + perm32(R & 31)) : R;
;         voffA[i] = (unsigned)(R * LD + C) * 2u; voffB[i] = (unsigned)(Rb * LD + C) * 2u; }
;     const size_t kstep = (size_t)(BK * 2);
;     const size_t hstep = (size_t)HALF * LD * 2;
;     const size_t tstep = 2 * hstep;
;     const unsigned ldsw = (unsigned)wid * 1024u;
;     const int aoff = lds_byte(wr * 64 + fr, fq * 8), boff = lds_byte(wc * 32 + fr, fq * 8);
;     ...
;     Unit cur, nxt; int ui = 0;
;     if (!S.next(0, cur)) return;
;     f32x4 acc[2][2][4][2];
; #pragma unroll
;     for (int a = 0; a < 2; ++a)
; #pragma unroll
;         for (int b = 0; b < 2; ++b)
; #pragma unroll
;             for (int m = 0; m < 4; ++m)
; #pragma unroll
;                 for (int n = 0; n < 2; ++n) acc[a][b][m][n] = (f32x4){0.f, 0.f, 0.f, 0.f};
;     bf16x8 At[4][2], B0[2][2], B1[2][2];
;     const char* cA = (const char*)g.A + (size_t)cur.pm * tstep; const char* cB = (const char*)g.Bt + (size_t)cur.pn * tstep;
;     S.a_ready(cur);
;     PG8_STAGE(PG8_SB(0, 0), cB, voffB); PG8_STAGE(PG8_SA(0, 0), cA, voffA); PG8_STAGE(PG8_SB(0, 1), cB + hstep, voffB); PG8_STAGE(PG8_SA(0, 1), cA + hstep, voffA);
;     if (wr == 1) PG8_BAR;
.LBB0_1332:
	s_and_b64 vcc, exec, s[2:3]
	s_cbranch_vccz .LBB0_1364
	s_mov_b32 s10, s87
	s_mov_b32 s36, s86
	s_add_u32 s37, s36, 0x2200000
	s_addc_u32 s40, s10, 0
	s_and_b64 s[0:1], s[34:35], exec
	s_cselect_b32 s0, 0x22000, 0
	s_add_u32 s0, s36, s0
	s_addc_u32 s1, s10, 0
	s_add_u32 s0, s0, 0x2060000
	s_addc_u32 s1, s1, 0
	s_add_u32 s2, s36, 0x5500000
	s_addc_u32 s3, s10, 0
	s_mov_b32 s41, s90
	v_mov_b32_e32 v0, v184
	s_cmpk_gt_i32 s41, 0x1ff
	v_readfirstlane_b32 s42, v0
	s_cbranch_scc1 .LBB0_1345
	v_lshlrev_b32_e32 v4, 4, v0
	v_add_u32_e32 v2, 0x2000, v4
	v_ashrrev_i32_e32 v1, 31, v2
	v_lshrrev_b32_e32 v1, 22, v1
	v_add_u32_e32 v1, v2, v1
	v_ashrrev_i32_e32 v1, 10, v1
	v_mul_i32_i24_e32 v3, 0x400, v1
	v_sub_u32_e32 v2, v2, v3
	v_lshrrev_b32_e32 v3, 4, v2
	v_bitop3_b32 v3, v3, v2, 32 bitop3:0x6c
	v_ashrrev_i32_e32 v2, 31, v3
	v_lshrrev_b32_e32 v2, 26, v2
	s_waitcnt lgkmcnt(0)
	v_add_u32_e32 v5, v3, v2
	v_lshlrev_b32_e32 v6, 3, v1
	v_ashrrev_i32_e32 v2, 6, v5
	v_and_b32_e32 v6, -16, v6
	v_add_u32_e32 v6, v2, v6
	v_and_b32_e32 v7, 3, v2
	s_mov_b32 s4, 0x1fffe0
	v_lshrrev_b32_e32 v8, 2, v6
	v_lshlrev_b32_e32 v9, 1, v6
	v_and_b32_e32 v5, 0xc0, v5
	v_and_or_b32 v7, v6, s4, v7
	v_and_b32_e32 v8, 4, v8
	v_and_b32_e32 v9, 24, v9
	v_sub_u32_e32 v3, v3, v5
	v_or3_b32 v7, v7, v8, v9
	v_lshlrev_b32_e32 v8, 5, v1
	v_ashrrev_i16_sdwa v3, v188, sext(v3) dst_sel:DWORD dst_unused:UNUSED_PAD src0_sel:DWORD src1_sel:BYTE_0
	v_and_b32_e32 v8, 32, v8
	v_bfe_i32 v3, v3, 0, 16
	v_add_lshl_u32 v5, v8, v3, 1
	v_lshl_add_u32 v148, v7, 11, v5
	v_lshl_add_u32 v150, v6, 11, v5
	v_bfe_i32 v5, v0, 27, 1
	v_lshrrev_b32_e32 v5, 22, v5
	v_add_u32_e32 v5, v4, v5
	v_and_b32_e32 v5, 0xfffffc00, v5
	v_sub_u32_e32 v4, v4, v5
	v_lshrrev_b32_e32 v5, 4, v4
	v_bitop3_b32 v6, v5, v4, 32 bitop3:0x6c
	v_ashrrev_i32_e32 v5, 31, v0
	v_lshrrev_b32_e32 v5, 26, v5
	v_ashrrev_i32_e32 v4, 31, v6
	v_add_u32_e32 v5, v0, v5
	v_lshrrev_b32_e32 v4, 26, v4
	v_ashrrev_i32_e32 v5, 6, v5
	v_add_u32_e32 v7, v6, v4
	v_lshlrev_b32_e32 v8, 3, v5
	v_ashrrev_i32_e32 v4, 6, v7
	v_and_b32_e32 v8, -16, v8
	v_add_u32_e32 v8, v4, v8
	v_and_b32_e32 v9, 3, v4
	s_ashr_i32 s44, s41, 31
	v_and_or_b32 v9, v8, s4, v9
	s_lshr_b32 s4, s44, 29
	s_add_i32 s4, s41, s4
	s_ashr_i32 s6, s42, 6
	s_ashr_i32 s7, s4, 3
	s_and_b32 s4, s4, -8
	s_ashr_i32 s5, s42, 8
	s_lshl_b32 s43, s6, 10
	s_sub_i32 s4, s41, s4
	s_cmp_lt_i32 s4, 0
	s_cselect_b32 s12, 0x41, 64
	s_mul_i32 s4, s12, s4
	s_add_i32 s4, s4, s7
	s_ashr_i32 s7, s4, 31
	s_lshr_b32 s7, s7, 26
	s_add_i32 s7, s4, s7
	s_ashr_i32 s12, s7, 6
	s_and_b32 s7, s7, 0xffc0
	s_sub_i32 s7, s4, s7
	s_bfe_i32 s4, s7, 0x80000
	s_bfe_u32 s4, s4, 0x3000c
	s_add_i32 s13, s7, s4
	s_bfe_i32 s4, s13, 0x80000
	s_and_b32 s13, s13, 0xf8
	s_sub_i32 s7, s7, s13
	s_lshl_b32 s12, s12, 3
	s_sext_i32_i16 s4, s4
	s_sext_i32_i8 s7, s7
	v_lshrrev_b32_e32 v10, 2, v8
	v_lshlrev_b32_e32 v11, 1, v8
	v_and_b32_e32 v7, 0xc0, v7
	s_lshr_b32 s4, s4, 3
	s_add_i32 s22, s12, s7
	v_and_b32_e32 v10, 4, v10
	v_and_b32_e32 v11, 24, v11
	v_sub_u32_e32 v6, v6, v7
	s_ashr_i32 s23, s22, 31
	s_bfe_i64 s[14:15], s[4:5], 0x100000
	v_or3_b32 v9, v9, v10, v11
	v_lshlrev_b32_e32 v10, 5, v5
	v_ashrrev_i16_sdwa v6, v188, sext(v6) dst_sel:DWORD dst_unused:UNUSED_PAD src0_sel:DWORD src1_sel:BYTE_0
	s_lshl_b64 s[12:13], s[22:23], 19
	s_lshl_b64 s[14:15], s[14:15], 19
	v_and_b32_e32 v10, 32, v10
	v_bfe_i32 v6, v6, 0, 16
	s_add_u32 s26, s36, s14
	v_add_lshl_u32 v7, v10, v6, 1
	s_addc_u32 s27, s10, s15
	s_add_i32 s23, s43, 0
	v_lshl_add_u32 v128, v9, 11, v7
	s_add_i32 m0, s23, 0x10000
	v_lshl_add_u32 v152, v8, 11, v7
	global_load_lds_dwordx4 v128, s[26:27]
	s_add_i32 m0, s23, 0x12000
	s_add_u32 s24, s37, s12
	global_load_lds_dwordx4 v148, s[26:27]
	s_addc_u32 s25, s40, s13
	s_mov_b32 m0, s23
	s_add_i32 s45, s23, 0x2000
	global_load_lds_dwordx4 v152, s[24:25]
	s_mov_b32 m0, s45
	s_add_u32 s12, s26, 0x40000
	global_load_lds_dwordx4 v150, s[24:25]
	s_addc_u32 s13, s27, 0
	s_add_i32 m0, s23, 0x14000
	s_nop 0
	global_load_lds_dwordx4 v128, s[12:13]
	s_add_i32 m0, s23, 0x16000
	s_nop 0
	global_load_lds_dwordx4 v148, s[12:13]
	s_add_u32 s12, s24, 0x40000
	s_addc_u32 s13, s25, 0
	s_add_i32 s46, s23, 0x4000
	s_mov_b32 m0, s46
	s_add_i32 s47, s23, 0x6000
	global_load_lds_dwordx4 v152, s[12:13]
	s_mov_b32 m0, s47
	s_cmp_lg_u32 s5, 1
	global_load_lds_dwordx4 v150, s[12:13]
	s_setprio 1
	s_cbranch_scc1 .LBB0_1336
	s_barrier
	s_setprio 0

; #define PG8_STAGE(bufoff, gbase, voff) do { _Pragma("unroll") for (int _i = 0; _i < 2; ++_i) \
;         __builtin_amdgcn_global_load_lds((const unsigned*)((const char*)(gbase) + (voff)[_i]), (PG8_LAS unsigned*)(lds + (bufoff) + ldsw + _i * 8192), 16, 0, 0); } while (0)
; #define PG8_BAR __builtin_amdgcn_s_barrier()
; template <class Epi, class Sched, bool STAMP = false>
; __device__ __forceinline__ void gemm_phase(PG8_LAS unsigned char* lds, const Gemm g, const Sched& S, const Epi& E, unsigned long long* stamps) {
;     ...
;     for (int i = 0; i < 2; ++i) { int R, C; stage_rc(tid * 16 + i * 8192, R, C); const int Rb = Epi::PERM ? ((R & ~31) + perm32(R & 31)) : R;
;         voffA[i] = (unsigned)(R * LD + C) * 2u; voffB[i] = (unsigned)(Rb * LD + C) * 2u; }
;     const size_t kstep = (size_t)(BK * 2);
;     const size_t hstep = (size_t)HALF * LD * 2;
;     const size_t tstep = 2 * hstep;
;     const unsigned ldsw = (unsigned)wid * 1024u;
;     const int aoff = lds_byte(wr * 64 + fr, fq * 8), boff = lds_byte(wc * 32 + fr, fq * 8);
;     ...
;     Unit cur, nxt; int ui = 0;
;     if (!S.next(0, cur)) return;
;     f32x4 acc[2][2][4][2];
; #pragma unroll
;     for (int a = 0; a < 2; ++a)
; #pragma unroll
;         for (int b = 0; b < 2; ++b)
; #pragma unroll
;             for (int m = 0; m < 4; ++m)
; #pragma unroll
;                 for (int n = 0; n < 2; ++n) acc[a][b][m][n] = (f32x4){0.f, 0.f, 0.f, 0.f};
;     bf16x8 At[4][2], B0[2][2], B1[2][2];
;     const char* cA = (const char*)g.A + (size_t)cur.pm * tstep; const char* cB = (const char*)g.Bt + (size_t)cur.pn * tstep;
;     S.a_ready(cur);
;     PG8_STAGE(PG8_SB(0, 0), cB, voffB); PG8_STAGE(PG8_SA(0, 0), cA, voffA); PG8_STAGE(PG8_SB(0, 1), cB + hstep, voffB); PG8_STAGE(PG8_SA(0, 1), cA + hstep, voffA);
;     if (wr == 1) PG8_BAR;
; __device__ __forceinline__ void run_rw_sample_tasks(LAS unsigned char* lds, unsigned char* ws) {
;     const int t = bidx(); OneUnit S; S.valid = t < 128; const int u = (t >> 2) & 31, sl = t & 3; S.pm = 64 + (u >> 3); S.pn = u & 7;
;     pg8::Gemm g; g.A = (const bf16_t*)(ws + OFF_XB) + sl * 256; g.Bt = (const bf16_t*)(ws + OFF_WRW) + sl * 256; g.M = T_ALL; g.N = 2048; g.K = 256; g.ld = 1024;
;     EpiPartial EA; EA.PART = (float*)(ws + OFF_GPART) + (size_t)sl * 1024 * 2048; EA.ldp = 2048;
;     pg8::gemm_phase<EpiPartial, OneUnit, false>(lds, g, S, EA, nullptr);
.LBB0_1345:
	s_add_u32 s4, s36, 0xbb00000
	s_mov_b32 s6, s90
	s_addc_u32 s5, s10, 0
	v_mov_b32_e32 v0, v184
	s_cmpk_gt_i32 s6, 0x7f
	s_nop 0
	v_readfirstlane_b32 s42, v0
	s_cbranch_scc1 .LBB0_1353
	v_lshlrev_b32_e32 v1, 4, v0
	v_add_u32_e32 v2, 0x2000, v1
	v_ashrrev_i32_e32 v3, 31, v2
	v_lshrrev_b32_e32 v3, 22, v3
	v_add_u32_e32 v3, v2, v3
	v_ashrrev_i32_e32 v3, 10, v3
	v_mul_i32_i24_e32 v4, 0x400, v3
	v_sub_u32_e32 v2, v2, v4
	v_lshrrev_b32_e32 v4, 4, v2
	v_bitop3_b32 v2, v4, v2, 32 bitop3:0x6c
	v_ashrrev_i32_e32 v4, 31, v2
	v_lshrrev_b32_e32 v4, 26, v4
	v_add_u32_e32 v4, v2, v4
	s_waitcnt lgkmcnt(0)
	v_lshrrev_b32_e32 v5, 6, v4
	v_lshlrev_b32_e32 v6, 3, v3
	v_and_b32_e32 v4, 0xc0, v4
	v_and_b32_e32 v6, 0x1ffff0, v6
	v_lshlrev_b32_e32 v3, 5, v3
	v_sub_u32_e32 v2, v2, v4
	v_add_u32_e32 v5, v5, v6
	v_and_b32_e32 v3, 32, v3
	v_ashrrev_i16_sdwa v2, v188, sext(v2) dst_sel:DWORD dst_unused:UNUSED_PAD src0_sel:DWORD src1_sel:BYTE_0
	v_lshl_or_b32 v3, v5, 10, v3
	v_bfe_i32 v2, v2, 0, 16
	v_add_lshl_u32 v148, v3, v2, 1
	v_bfe_i32 v2, v0, 27, 1
	v_lshrrev_b32_e32 v2, 22, v2
	v_add_u32_e32 v2, v1, v2
	v_and_b32_e32 v2, 0xfffffc00, v2
	v_sub_u32_e32 v1, v1, v2
	v_lshrrev_b32_e32 v2, 4, v1
	s_and_b32 s45, s6, 3
	s_bfe_u32 s7, s6, 0x20005
	s_ashr_i32 s14, s42, 6
	v_bitop3_b32 v1, v2, v1, 32 bitop3:0x6c
	v_ashrrev_i32_e32 v4, 31, v0
	s_or_b32 s44, s7, 64
	s_bfe_u32 s43, s6, 0x30002
	s_ashr_i32 s15, s42, 8
	s_lshl_b32 s46, s14, 10
	s_lshl_b32 s6, s45, 9
	v_ashrrev_i32_e32 v2, 31, v1
	v_lshrrev_b32_e32 v4, 26, v4
	s_add_u32 s7, s36, s6
	v_lshrrev_b32_e32 v2, 26, v2
	v_add_u32_e32 v4, v0, v4
	s_addc_u32 s10, s10, 0
	v_add_u32_e32 v2, v1, v2
	v_ashrrev_i32_e32 v4, 6, v4
	s_add_u32 s12, s37, s6
	v_lshrrev_b32_e32 v3, 6, v2
	v_lshlrev_b32_e32 v5, 3, v4
	v_and_b32_e32 v2, 0xc0, v2
	s_addc_u32 s13, s40, 0
	v_and_b32_e32 v5, 0x1ffff0, v5
	v_lshlrev_b32_e32 v4, 5, v4
	v_sub_u32_e32 v1, v1, v2
	s_lshl_b32 s16, s44, 19
	s_lshl_b32 s6, s43, 19
	v_add_u32_e32 v3, v3, v5
	v_and_b32_e32 v4, 32, v4
	v_ashrrev_i16_sdwa v1, v188, sext(v1) dst_sel:DWORD dst_unused:UNUSED_PAD src0_sel:DWORD src1_sel:BYTE_0
	s_add_u32 s6, s7, s6
	v_lshl_or_b32 v3, v3, 10, v4
	v_bfe_i32 v1, v1, 0, 16
	s_addc_u32 s7, s10, 0
	s_add_i32 s10, s46, 0
	v_add_lshl_u32 v128, v3, v1, 1
	s_add_i32 m0, s10, 0x10000
	s_nop 0
	global_load_lds_dwordx4 v128, s[6:7]
	s_add_i32 m0, s10, 0x12000
	s_add_u32 s12, s12, s16
	global_load_lds_dwordx4 v148, s[6:7]
	s_addc_u32 s13, s13, 0
	s_mov_b32 m0, s10
	s_add_i32 s47, s10, 0x2000
	global_load_lds_dwordx4 v128, s[12:13]
	s_mov_b32 m0, s47
	s_add_u32 s16, s6, 0x40000
	global_load_lds_dwordx4 v148, s[12:13]
	s_addc_u32 s17, s7, 0
	s_add_i32 m0, s10, 0x14000
	s_nop 0
	global_load_lds_dwordx4 v128, s[16:17]
	s_add_i32 m0, s10, 0x16000
	s_add_u32 s20, s12, 0x40000
	s_addc_u32 s21, s13, 0
	s_add_i32 s48, s10, 0x4000
	global_load_lds_dwordx4 v148, s[16:17]
	s_mov_b32 m0, s48
	s_add_i32 s49, s10, 0x6000
	global_load_lds_dwordx4 v128, s[20:21]
	s_mov_b32 m0, s49
	s_cmp_lg_u32 s15, 1
	global_load_lds_dwordx4 v148, s[20:21]
	s_setprio 1
	s_cbranch_scc1 .LBB0_1348
	s_barrier
	s_setprio 0
